# v26 plus write-through sc1 on the 136 GEMM epilogue dwordx4 stores so the grid barrier L2 writeback has little dirty data left
# speedup vs baseline: 1.0019x; 1.0019x over previous
.LBB0_316:
	v_lshl_or_b32 v140, s71, 8, v144
	v_add_u32_e32 v148, s72, v142
	v_ashrrev_i32_e32 v141, 31, v140
	v_lshl_add_u64 v[140:141], v[140:141], 1, s[42:43]
	v_mad_i64_i32 v[146:147], s[42:43], v148, s68, 0
	v_lshl_add_u64 v[146:147], v[146:147], 1, v[140:141]
	v_cvt_pk_bf16_f32 v126, v126, v127
	v_cvt_pk_bf16_f32 v127, v128, v129
	v_cvt_pk_bf16_f32 v128, v122, v123
	v_cvt_pk_bf16_f32 v129, v124, v125
	global_store_dwordx4 v[146:147], v[126:129], off sc1
	v_cvt_pk_bf16_f32 v114, v114, v115
	v_cvt_pk_bf16_f32 v115, v116, v117
	v_cvt_pk_bf16_f32 v116, v106, v107
	v_add_u32_e32 v106, 16, v148
	v_mad_i64_i32 v[106:107], s[42:43], v106, s68, 0
	v_cvt_pk_bf16_f32 v117, v108, v109
	global_store_dwordx4 v[146:147], v[114:117], off offset:256 sc1
	s_and_b64 vcc, exec, s[6:7]
	s_mov_b64 s[6:7], -1
	v_lshl_add_u64 v[114:115], v[106:107], 1, v[140:141]
	v_cvt_pk_bf16_f32 v106, v118, v119
	v_cvt_pk_bf16_f32 v107, v120, v121
	v_cvt_pk_bf16_f32 v108, v110, v111
	v_cvt_pk_bf16_f32 v109, v112, v113
	global_store_dwordx4 v[114:115], v[106:109], off sc1
	v_cvt_pk_bf16_f32 v98, v98, v99
	v_cvt_pk_bf16_f32 v99, v100, v101
	v_cvt_pk_bf16_f32 v100, v90, v91
	v_add_u32_e32 v90, 32, v148
	v_mad_i64_i32 v[90:91], s[42:43], v90, s68, 0
	v_cvt_pk_bf16_f32 v101, v92, v93
	global_store_dwordx4 v[114:115], v[98:101], off offset:256 sc1
	s_nop 1
	v_lshl_add_u64 v[98:99], v[90:91], 1, v[140:141]
	v_cvt_pk_bf16_f32 v90, v102, v103
	v_cvt_pk_bf16_f32 v91, v104, v105
	v_cvt_pk_bf16_f32 v92, v94, v95
	v_cvt_pk_bf16_f32 v93, v96, v97
	global_store_dwordx4 v[98:99], v[90:93], off sc1
	v_cvt_pk_bf16_f32 v82, v82, v83
	v_cvt_pk_bf16_f32 v83, v84, v85
	v_cvt_pk_bf16_f32 v84, v74, v75
	v_add_u32_e32 v74, 48, v148
	v_mad_i64_i32 v[74:75], s[42:43], v74, s68, 0
	v_cvt_pk_bf16_f32 v85, v76, v77
	global_store_dwordx4 v[98:99], v[82:85], off offset:256 sc1
	s_nop 1
	v_lshl_add_u64 v[82:83], v[74:75], 1, v[140:141]
	v_cvt_pk_bf16_f32 v74, v86, v87
	v_cvt_pk_bf16_f32 v75, v88, v89
	v_cvt_pk_bf16_f32 v76, v78, v79
	v_cvt_pk_bf16_f32 v77, v80, v81
	global_store_dwordx4 v[82:83], v[74:77], off sc1
	v_cvt_pk_bf16_f32 v70, v70, v71
	v_cvt_pk_bf16_f32 v71, v72, v73
	v_cvt_pk_bf16_f32 v72, v66, v67
	v_add_u32_e32 v66, 0x80, v148
	v_mad_i64_i32 v[66:67], s[42:43], v66, s68, 0
	v_lshl_add_u64 v[66:67], v[66:67], 1, v[140:141]
	v_cvt_pk_bf16_f32 v73, v68, v69
	global_store_dwordx4 v[82:83], v[70:73], off offset:256 sc1
	v_cvt_pk_bf16_f32 v62, v62, v63
	v_cvt_pk_bf16_f32 v63, v64, v65
	v_cvt_pk_bf16_f32 v64, v58, v59
	v_cvt_pk_bf16_f32 v65, v60, v61
	global_store_dwordx4 v[66:67], v[62:65], off sc1
	v_cvt_pk_bf16_f32 v50, v50, v51
	v_cvt_pk_bf16_f32 v51, v52, v53
	v_cvt_pk_bf16_f32 v52, v42, v43
	v_add_u32_e32 v42, 0x90, v148
	v_mad_i64_i32 v[42:43], s[42:43], v42, s68, 0
	v_cvt_pk_bf16_f32 v53, v44, v45
	global_store_dwordx4 v[66:67], v[50:53], off offset:256 sc1
	s_nop 1
	v_lshl_add_u64 v[50:51], v[42:43], 1, v[140:141]
	v_cvt_pk_bf16_f32 v42, v54, v55
	v_cvt_pk_bf16_f32 v43, v56, v57
	v_cvt_pk_bf16_f32 v44, v46, v47
	v_cvt_pk_bf16_f32 v45, v48, v49
	global_store_dwordx4 v[50:51], v[42:45], off sc1
	v_cvt_pk_bf16_f32 v34, v34, v35
	v_cvt_pk_bf16_f32 v35, v36, v37
	v_cvt_pk_bf16_f32 v36, v26, v27
	v_add_u32_e32 v26, 0xa0, v148
	v_mad_i64_i32 v[26:27], s[42:43], v26, s68, 0
	v_cvt_pk_bf16_f32 v37, v28, v29
	global_store_dwordx4 v[50:51], v[34:37], off offset:256 sc1
	s_nop 1
	v_lshl_add_u64 v[34:35], v[26:27], 1, v[140:141]
	v_cvt_pk_bf16_f32 v26, v38, v39
	v_cvt_pk_bf16_f32 v27, v40, v41
	v_cvt_pk_bf16_f32 v28, v30, v31
	v_cvt_pk_bf16_f32 v29, v32, v33
	global_store_dwordx4 v[34:35], v[26:29], off sc1
	v_cvt_pk_bf16_f32 v18, v18, v19
	v_cvt_pk_bf16_f32 v19, v20, v21
	v_cvt_pk_bf16_f32 v20, v10, v11
	v_add_u32_e32 v10, 0xb0, v148
	v_mad_i64_i32 v[10:11], s[42:43], v10, s68, 0
	v_cvt_pk_bf16_f32 v21, v12, v13
	global_store_dwordx4 v[34:35], v[18:21], off offset:256 sc1
	s_nop 1
	v_lshl_add_u64 v[18:19], v[10:11], 1, v[140:141]
	v_cvt_pk_bf16_f32 v10, v22, v23
	v_cvt_pk_bf16_f32 v11, v24, v25
	v_cvt_pk_bf16_f32 v12, v14, v15
	v_cvt_pk_bf16_f32 v13, v16, v17
	global_store_dwordx4 v[18:19], v[10:13], off sc1
	v_cvt_pk_bf16_f32 v6, v6, v7
	v_cvt_pk_bf16_f32 v7, v8, v9
	v_cvt_pk_bf16_f32 v8, v2, v3
	v_cvt_pk_bf16_f32 v9, v4, v5
	global_store_dwordx4 v[18:19], v[6:9], off offset:256 sc1
	s_cbranch_vccnz .LBB0_296
	s_andn2_b64 vcc, exec, s[36:37]
	s_cbranch_vccnz .LBB0_295
	s_barrier
	s_branch .LBB0_295

.LBB0_357:
	v_lshl_add_u32 v144, s57, 8, v139
	v_mov_b64_e32 v[146:147], s[12:13]
	v_or_b32_e32 v151, s59, v138
	v_mad_i64_i32 v[146:147], s[58:59], v144, s68, v[146:147]
	s_ashr_i32 s37, s36, 31
	s_and_b64 s[58:59], s[20:21], s[8:9]
	v_lshl_add_u64 v[146:147], s[36:37], 1, v[146:147]
	v_cndmask_b32_e64 v150, 0, 1, s[58:59]
	v_ashrrev_i32_e32 v145, 31, v144
	v_lshl_add_u64 v[146:147], v[146:147], 0, v[0:1]
	v_cmp_ne_u32_e64 s[8:9], 1, v150
	s_andn2_b64 vcc, exec, s[58:59]
	v_ashrrev_i32_e32 v150, 31, v151
	v_cvt_pk_bf16_f32 v152, v126, v127
	v_cvt_pk_bf16_f32 v153, v128, v129
	v_cvt_pk_bf16_f32 v154, v122, v123
	v_cvt_pk_bf16_f32 v155, v124, v125
	global_store_dwordx4 v[146:147], v[152:155], off sc1
	s_cbranch_vccnz .LBB0_359
	s_nop 0
	v_mad_u64_u32 v[152:153], s[58:59], v151, s16, 0
	v_mov_b32_e32 v154, v153
	v_mad_u64_u32 v[154:155], s[58:59], v150, s16, v[154:155]
	v_mov_b32_e32 v153, v154
	v_lshl_add_u64 v[152:153], v[152:153], 2, s[14:15]
	v_lshl_add_u64 v[152:153], v[144:145], 2, v[152:153]
	global_store_dword v[152:153], v126, off
	v_lshl_add_u64 v[152:153], v[152:153], 0, s[28:29]
	global_store_dword v[152:153], v122, off
	v_lshl_add_u64 v[152:153], v[152:153], 0, s[34:35]
	global_store_dword v[152:153], v127, off
	v_lshl_add_u64 v[126:127], v[152:153], 0, s[28:29]
	global_store_dword v[126:127], v123, off
	v_lshl_add_u64 v[122:123], v[126:127], 0, s[34:35]
	global_store_dword v[122:123], v128, off
	v_lshl_add_u64 v[122:123], v[122:123], 0, s[28:29]
	global_store_dword v[122:123], v124, off
	v_lshl_add_u64 v[122:123], v[122:123], 0, s[34:35]
	global_store_dword v[122:123], v129, off
	v_lshl_add_u64 v[122:123], v[122:123], 0, s[28:29]
	global_store_dword v[122:123], v125, off
.LBB0_359:
	v_cvt_pk_bf16_f32 v122, v118, v119
	v_cvt_pk_bf16_f32 v123, v120, v121
	v_cvt_pk_bf16_f32 v124, v114, v115
	v_cvt_pk_bf16_f32 v125, v116, v117
	global_store_dwordx4 v[146:147], v[122:125], off offset:256 sc1
	s_and_b64 vcc, exec, s[8:9]
	s_nop 0
	v_or_b32_e32 v122, 0x80, v151
	s_cbranch_vccnz .LBB0_361
	v_mad_u64_u32 v[124:125], s[58:59], v122, s16, 0
	v_mov_b32_e32 v126, v125
	v_mad_u64_u32 v[126:127], s[58:59], v150, s16, v[126:127]
	v_mov_b32_e32 v125, v126
	v_lshl_add_u64 v[124:125], v[124:125], 2, s[14:15]
	v_lshl_add_u64 v[124:125], v[144:145], 2, v[124:125]
	global_store_dword v[124:125], v118, off
	v_lshl_add_u64 v[124:125], v[124:125], 0, s[28:29]
	global_store_dword v[124:125], v114, off
	v_lshl_add_u64 v[124:125], v[124:125], 0, s[34:35]
	global_store_dword v[124:125], v119, off
	v_lshl_add_u64 v[118:119], v[124:125], 0, s[28:29]
	global_store_dword v[118:119], v115, off
	v_lshl_add_u64 v[114:115], v[118:119], 0, s[34:35]
	global_store_dword v[114:115], v120, off
	v_lshl_add_u64 v[114:115], v[114:115], 0, s[28:29]
	global_store_dword v[114:115], v116, off
	v_lshl_add_u64 v[114:115], v[114:115], 0, s[34:35]
	global_store_dword v[114:115], v121, off
	v_lshl_add_u64 v[114:115], v[114:115], 0, s[28:29]
	global_store_dword v[114:115], v117, off
.LBB0_361:
	v_or_b32_e32 v116, 16, v144
	v_mov_b64_e32 v[114:115], s[12:13]
	v_mad_i64_i32 v[114:115], s[58:59], v116, s68, v[114:115]
	v_lshl_add_u64 v[114:115], s[36:37], 1, v[114:115]
	v_lshl_add_u64 v[114:115], v[114:115], 0, v[0:1]
	s_and_b64 vcc, exec, s[8:9]
	v_cvt_pk_bf16_f32 v116, v110, v111
	v_cvt_pk_bf16_f32 v117, v112, v113
	v_cvt_pk_bf16_f32 v118, v106, v107
	v_cvt_pk_bf16_f32 v119, v108, v109
	global_store_dwordx4 v[114:115], v[116:119], off sc1
	s_cbranch_vccnz .LBB0_363
	s_nop 0
	v_mad_u64_u32 v[116:117], s[58:59], v151, s16, 0
	v_mov_b32_e32 v118, v117
	v_mad_u64_u32 v[118:119], s[58:59], v150, s16, v[118:119]
	v_mov_b32_e32 v117, v118
	v_lshl_add_u64 v[116:117], v[116:117], 2, s[14:15]
	v_lshl_add_u64 v[116:117], v[144:145], 2, v[116:117]
	global_store_dword v[116:117], v110, off offset:64
	v_lshl_add_u64 v[116:117], v[116:117], 0, s[28:29]
	global_store_dword v[116:117], v106, off offset:64
	v_lshl_add_u64 v[116:117], v[116:117], 0, s[34:35]
	global_store_dword v[116:117], v111, off offset:64
	v_lshl_add_u64 v[110:111], v[116:117], 0, s[28:29]
	global_store_dword v[110:111], v107, off offset:64
	v_lshl_add_u64 v[106:107], v[110:111], 0, s[34:35]
	global_store_dword v[106:107], v112, off offset:64
	v_lshl_add_u64 v[106:107], v[106:107], 0, s[28:29]
	global_store_dword v[106:107], v108, off offset:64
	v_lshl_add_u64 v[106:107], v[106:107], 0, s[34:35]
	global_store_dword v[106:107], v113, off offset:64
	v_lshl_add_u64 v[106:107], v[106:107], 0, s[28:29]
	global_store_dword v[106:107], v109, off offset:64
.LBB0_363:
	s_and_b64 vcc, exec, s[8:9]
	v_cvt_pk_bf16_f32 v106, v102, v103
	v_cvt_pk_bf16_f32 v107, v104, v105
	v_cvt_pk_bf16_f32 v108, v98, v99
	v_cvt_pk_bf16_f32 v109, v100, v101
	global_store_dwordx4 v[114:115], v[106:109], off offset:256 sc1
	s_cbranch_vccnz .LBB0_365
	s_nop 0
	v_mad_u64_u32 v[106:107], s[58:59], v122, s16, 0
	v_mov_b32_e32 v108, v107
	v_mad_u64_u32 v[108:109], s[58:59], v150, s16, v[108:109]
	v_mov_b32_e32 v107, v108
	v_lshl_add_u64 v[106:107], v[106:107], 2, s[14:15]
	v_lshl_add_u64 v[106:107], v[144:145], 2, v[106:107]
	global_store_dword v[106:107], v102, off offset:64
	v_lshl_add_u64 v[106:107], v[106:107], 0, s[28:29]
	global_store_dword v[106:107], v98, off offset:64
	v_lshl_add_u64 v[106:107], v[106:107], 0, s[34:35]
	global_store_dword v[106:107], v103, off offset:64
	v_lshl_add_u64 v[102:103], v[106:107], 0, s[28:29]
	global_store_dword v[102:103], v99, off offset:64
	v_lshl_add_u64 v[98:99], v[102:103], 0, s[34:35]
	global_store_dword v[98:99], v104, off offset:64
	v_lshl_add_u64 v[98:99], v[98:99], 0, s[28:29]
	global_store_dword v[98:99], v100, off offset:64
	v_lshl_add_u64 v[98:99], v[98:99], 0, s[34:35]
	global_store_dword v[98:99], v105, off offset:64
	v_lshl_add_u64 v[98:99], v[98:99], 0, s[28:29]
	global_store_dword v[98:99], v101, off offset:64
.LBB0_365:
	v_or_b32_e32 v100, 32, v144
	v_mov_b64_e32 v[98:99], s[12:13]
	v_mad_i64_i32 v[98:99], s[58:59], v100, s68, v[98:99]
	v_lshl_add_u64 v[98:99], s[36:37], 1, v[98:99]
	v_lshl_add_u64 v[98:99], v[98:99], 0, v[0:1]
	s_and_b64 vcc, exec, s[8:9]
	v_cvt_pk_bf16_f32 v100, v94, v95
	v_cvt_pk_bf16_f32 v101, v96, v97
	v_cvt_pk_bf16_f32 v102, v90, v91
	v_cvt_pk_bf16_f32 v103, v92, v93
	global_store_dwordx4 v[98:99], v[100:103], off sc1
	s_cbranch_vccnz .LBB0_367
	s_nop 0
	v_mad_u64_u32 v[100:101], s[58:59], v151, s16, 0
	v_mov_b32_e32 v102, v101
	v_mad_u64_u32 v[102:103], s[58:59], v150, s16, v[102:103]
	v_mov_b32_e32 v101, v102
	v_lshl_add_u64 v[100:101], v[100:101], 2, s[14:15]
	v_lshl_add_u64 v[100:101], v[144:145], 2, v[100:101]
	global_store_dword v[100:101], v94, off offset:128
	v_lshl_add_u64 v[100:101], v[100:101], 0, s[28:29]
	global_store_dword v[100:101], v90, off offset:128
	v_lshl_add_u64 v[100:101], v[100:101], 0, s[34:35]
	global_store_dword v[100:101], v95, off offset:128
	v_lshl_add_u64 v[94:95], v[100:101], 0, s[28:29]
	global_store_dword v[94:95], v91, off offset:128
	v_lshl_add_u64 v[90:91], v[94:95], 0, s[34:35]
	global_store_dword v[90:91], v96, off offset:128
	v_lshl_add_u64 v[90:91], v[90:91], 0, s[28:29]
	global_store_dword v[90:91], v92, off offset:128
	v_lshl_add_u64 v[90:91], v[90:91], 0, s[34:35]
	global_store_dword v[90:91], v97, off offset:128
	v_lshl_add_u64 v[90:91], v[90:91], 0, s[28:29]
	global_store_dword v[90:91], v93, off offset:128
.LBB0_367:
	s_and_b64 vcc, exec, s[8:9]
	v_cvt_pk_bf16_f32 v90, v86, v87
	v_cvt_pk_bf16_f32 v91, v88, v89
	v_cvt_pk_bf16_f32 v92, v82, v83
	v_cvt_pk_bf16_f32 v93, v84, v85
	global_store_dwordx4 v[98:99], v[90:93], off offset:256 sc1
	s_cbranch_vccnz .LBB0_369
	s_nop 0
	v_mad_u64_u32 v[90:91], s[58:59], v122, s16, 0
	v_mov_b32_e32 v92, v91
	v_mad_u64_u32 v[92:93], s[58:59], v150, s16, v[92:93]
	v_mov_b32_e32 v91, v92
	v_lshl_add_u64 v[90:91], v[90:91], 2, s[14:15]
	v_lshl_add_u64 v[90:91], v[144:145], 2, v[90:91]
	global_store_dword v[90:91], v86, off offset:128
	v_lshl_add_u64 v[90:91], v[90:91], 0, s[28:29]
	global_store_dword v[90:91], v82, off offset:128
	v_lshl_add_u64 v[90:91], v[90:91], 0, s[34:35]
	global_store_dword v[90:91], v87, off offset:128
	v_lshl_add_u64 v[86:87], v[90:91], 0, s[28:29]
	global_store_dword v[86:87], v83, off offset:128
	v_lshl_add_u64 v[82:83], v[86:87], 0, s[34:35]
	global_store_dword v[82:83], v88, off offset:128
	v_lshl_add_u64 v[82:83], v[82:83], 0, s[28:29]
	global_store_dword v[82:83], v84, off offset:128
	v_lshl_add_u64 v[82:83], v[82:83], 0, s[34:35]
	global_store_dword v[82:83], v89, off offset:128
	v_lshl_add_u64 v[82:83], v[82:83], 0, s[28:29]
	global_store_dword v[82:83], v85, off offset:128
.LBB0_369:
	v_or_b32_e32 v84, 48, v144
	v_mov_b64_e32 v[82:83], s[12:13]
	v_mad_i64_i32 v[82:83], s[58:59], v84, s68, v[82:83]
	v_lshl_add_u64 v[82:83], s[36:37], 1, v[82:83]
	v_lshl_add_u64 v[82:83], v[82:83], 0, v[0:1]
	s_and_b64 vcc, exec, s[8:9]
	v_cvt_pk_bf16_f32 v84, v78, v79
	v_cvt_pk_bf16_f32 v85, v80, v81
	v_cvt_pk_bf16_f32 v86, v74, v75
	v_cvt_pk_bf16_f32 v87, v76, v77
	global_store_dwordx4 v[82:83], v[84:87], off sc1
	s_cbranch_vccnz .LBB0_371
	s_nop 0
	v_mad_u64_u32 v[84:85], s[58:59], v151, s16, 0
	v_mov_b32_e32 v86, v85
	v_mad_u64_u32 v[86:87], s[58:59], v150, s16, v[86:87]
	v_mov_b32_e32 v85, v86
	v_lshl_add_u64 v[84:85], v[84:85], 2, s[14:15]
	v_lshl_add_u64 v[84:85], v[144:145], 2, v[84:85]
	global_store_dword v[84:85], v78, off offset:192
	v_lshl_add_u64 v[84:85], v[84:85], 0, s[28:29]
	global_store_dword v[84:85], v74, off offset:192
	v_lshl_add_u64 v[84:85], v[84:85], 0, s[34:35]
	global_store_dword v[84:85], v79, off offset:192
	v_lshl_add_u64 v[78:79], v[84:85], 0, s[28:29]
	global_store_dword v[78:79], v75, off offset:192
	v_lshl_add_u64 v[74:75], v[78:79], 0, s[34:35]
	global_store_dword v[74:75], v80, off offset:192
	v_lshl_add_u64 v[74:75], v[74:75], 0, s[28:29]
	global_store_dword v[74:75], v76, off offset:192
	v_lshl_add_u64 v[74:75], v[74:75], 0, s[34:35]
	global_store_dword v[74:75], v81, off offset:192
	v_lshl_add_u64 v[74:75], v[74:75], 0, s[28:29]
	global_store_dword v[74:75], v77, off offset:192
.LBB0_371:
	s_and_b64 vcc, exec, s[8:9]
	v_cvt_pk_bf16_f32 v74, v70, v71
	v_cvt_pk_bf16_f32 v75, v72, v73
	v_cvt_pk_bf16_f32 v76, v66, v67
	v_cvt_pk_bf16_f32 v77, v68, v69
	global_store_dwordx4 v[82:83], v[74:77], off offset:256 sc1
	s_cbranch_vccnz .LBB0_373
	s_nop 0
	v_mad_u64_u32 v[74:75], s[58:59], v122, s16, 0
	v_mov_b32_e32 v76, v75
	v_mad_u64_u32 v[76:77], s[58:59], v150, s16, v[76:77]
	v_mov_b32_e32 v75, v76
	v_lshl_add_u64 v[74:75], v[74:75], 2, s[14:15]
	v_lshl_add_u64 v[74:75], v[144:145], 2, v[74:75]
	global_store_dword v[74:75], v70, off offset:192
	v_lshl_add_u64 v[74:75], v[74:75], 0, s[28:29]
	global_store_dword v[74:75], v66, off offset:192
	v_lshl_add_u64 v[74:75], v[74:75], 0, s[34:35]
	global_store_dword v[74:75], v71, off offset:192
	v_lshl_add_u64 v[70:71], v[74:75], 0, s[28:29]
	global_store_dword v[70:71], v67, off offset:192
	v_lshl_add_u64 v[66:67], v[70:71], 0, s[34:35]
	global_store_dword v[66:67], v72, off offset:192
	v_lshl_add_u64 v[66:67], v[66:67], 0, s[28:29]
	global_store_dword v[66:67], v68, off offset:192
	v_lshl_add_u64 v[66:67], v[66:67], 0, s[34:35]
	global_store_dword v[66:67], v73, off offset:192
	v_lshl_add_u64 v[66:67], v[66:67], 0, s[28:29]
	global_store_dword v[66:67], v69, off offset:192
.LBB0_373:
	v_add_u32_e32 v68, 0x80, v144
	v_mov_b64_e32 v[66:67], s[12:13]
	v_mad_i64_i32 v[66:67], s[58:59], v68, s68, v[66:67]
	v_lshl_add_u64 v[66:67], s[36:37], 1, v[66:67]
	v_lshl_add_u64 v[66:67], v[66:67], 0, v[0:1]
	s_and_b64 vcc, exec, s[8:9]
	v_cvt_pk_bf16_f32 v68, v62, v63
	v_cvt_pk_bf16_f32 v69, v64, v65
	v_cvt_pk_bf16_f32 v70, v58, v59
	v_cvt_pk_bf16_f32 v71, v60, v61
	global_store_dwordx4 v[66:67], v[68:71], off sc1
	s_cbranch_vccnz .LBB0_375
	s_nop 0
	v_mad_u64_u32 v[68:69], s[58:59], v151, s16, 0
	v_mov_b32_e32 v70, v69
	v_mad_u64_u32 v[70:71], s[58:59], v150, s16, v[70:71]
	v_mov_b32_e32 v69, v70
	v_lshl_add_u64 v[68:69], v[68:69], 2, s[14:15]
	v_lshl_add_u64 v[68:69], v[144:145], 2, v[68:69]
	global_store_dword v[68:69], v62, off offset:512
	v_lshl_add_u64 v[68:69], v[68:69], 0, s[28:29]
	global_store_dword v[68:69], v58, off offset:512
	v_lshl_add_u64 v[68:69], v[68:69], 0, s[34:35]
	global_store_dword v[68:69], v63, off offset:512
	v_lshl_add_u64 v[62:63], v[68:69], 0, s[28:29]
	global_store_dword v[62:63], v59, off offset:512
	v_lshl_add_u64 v[58:59], v[62:63], 0, s[34:35]
	global_store_dword v[58:59], v64, off offset:512
	v_lshl_add_u64 v[58:59], v[58:59], 0, s[28:29]
	global_store_dword v[58:59], v60, off offset:512
	v_lshl_add_u64 v[58:59], v[58:59], 0, s[34:35]
	global_store_dword v[58:59], v65, off offset:512
	v_lshl_add_u64 v[58:59], v[58:59], 0, s[28:29]
	global_store_dword v[58:59], v61, off offset:512
.LBB0_375:
	s_and_b64 vcc, exec, s[8:9]
	v_cvt_pk_bf16_f32 v58, v54, v55
	v_cvt_pk_bf16_f32 v59, v56, v57
	v_cvt_pk_bf16_f32 v60, v50, v51
	v_cvt_pk_bf16_f32 v61, v52, v53
	global_store_dwordx4 v[66:67], v[58:61], off offset:256 sc1
	s_cbranch_vccnz .LBB0_377
	s_nop 0
	v_mad_u64_u32 v[58:59], s[58:59], v122, s16, 0
	v_mov_b32_e32 v60, v59
	v_mad_u64_u32 v[60:61], s[58:59], v150, s16, v[60:61]
	v_mov_b32_e32 v59, v60
	v_lshl_add_u64 v[58:59], v[58:59], 2, s[14:15]
	v_lshl_add_u64 v[58:59], v[144:145], 2, v[58:59]
	global_store_dword v[58:59], v54, off offset:512
	v_lshl_add_u64 v[58:59], v[58:59], 0, s[28:29]
	global_store_dword v[58:59], v50, off offset:512
	v_lshl_add_u64 v[58:59], v[58:59], 0, s[34:35]
	global_store_dword v[58:59], v55, off offset:512
	v_lshl_add_u64 v[54:55], v[58:59], 0, s[28:29]
	global_store_dword v[54:55], v51, off offset:512
	v_lshl_add_u64 v[50:51], v[54:55], 0, s[34:35]
	global_store_dword v[50:51], v56, off offset:512
	v_lshl_add_u64 v[50:51], v[50:51], 0, s[28:29]
	global_store_dword v[50:51], v52, off offset:512
	v_lshl_add_u64 v[50:51], v[50:51], 0, s[34:35]
	global_store_dword v[50:51], v57, off offset:512
	v_lshl_add_u64 v[50:51], v[50:51], 0, s[28:29]
	global_store_dword v[50:51], v53, off offset:512
.LBB0_377:
	v_add_u32_e32 v52, 0x90, v144
	v_mov_b64_e32 v[50:51], s[12:13]
	v_mad_i64_i32 v[50:51], s[58:59], v52, s68, v[50:51]
	v_lshl_add_u64 v[50:51], s[36:37], 1, v[50:51]
	v_lshl_add_u64 v[50:51], v[50:51], 0, v[0:1]
	s_and_b64 vcc, exec, s[8:9]
	v_cvt_pk_bf16_f32 v52, v46, v47
	v_cvt_pk_bf16_f32 v53, v48, v49
	v_cvt_pk_bf16_f32 v54, v42, v43
	v_cvt_pk_bf16_f32 v55, v44, v45
	global_store_dwordx4 v[50:51], v[52:55], off sc1
	s_cbranch_vccnz .LBB0_379
	s_nop 0
	v_mad_u64_u32 v[52:53], s[58:59], v151, s16, 0
	v_mov_b32_e32 v54, v53
	v_mad_u64_u32 v[54:55], s[58:59], v150, s16, v[54:55]
	v_mov_b32_e32 v53, v54
	v_lshl_add_u64 v[52:53], v[52:53], 2, s[14:15]
	v_lshl_add_u64 v[52:53], v[144:145], 2, v[52:53]
	global_store_dword v[52:53], v46, off offset:576
	v_lshl_add_u64 v[52:53], v[52:53], 0, s[28:29]
	global_store_dword v[52:53], v42, off offset:576
	v_lshl_add_u64 v[52:53], v[52:53], 0, s[34:35]
	global_store_dword v[52:53], v47, off offset:576
	v_lshl_add_u64 v[46:47], v[52:53], 0, s[28:29]
	global_store_dword v[46:47], v43, off offset:576
	v_lshl_add_u64 v[42:43], v[46:47], 0, s[34:35]
	global_store_dword v[42:43], v48, off offset:576
	v_lshl_add_u64 v[42:43], v[42:43], 0, s[28:29]
	global_store_dword v[42:43], v44, off offset:576
	v_lshl_add_u64 v[42:43], v[42:43], 0, s[34:35]
	global_store_dword v[42:43], v49, off offset:576
	v_lshl_add_u64 v[42:43], v[42:43], 0, s[28:29]
	global_store_dword v[42:43], v45, off offset:576
.LBB0_379:
	s_and_b64 vcc, exec, s[8:9]
	v_cvt_pk_bf16_f32 v42, v38, v39
	v_cvt_pk_bf16_f32 v43, v40, v41
	v_cvt_pk_bf16_f32 v44, v34, v35
	v_cvt_pk_bf16_f32 v45, v36, v37
	global_store_dwordx4 v[50:51], v[42:45], off offset:256 sc1
	s_cbranch_vccnz .LBB0_381
	s_nop 0
	v_mad_u64_u32 v[42:43], s[58:59], v122, s16, 0
	v_mov_b32_e32 v44, v43
	v_mad_u64_u32 v[44:45], s[58:59], v150, s16, v[44:45]
	v_mov_b32_e32 v43, v44
	v_lshl_add_u64 v[42:43], v[42:43], 2, s[14:15]
	v_lshl_add_u64 v[42:43], v[144:145], 2, v[42:43]
	global_store_dword v[42:43], v38, off offset:576
	v_lshl_add_u64 v[42:43], v[42:43], 0, s[28:29]
	global_store_dword v[42:43], v34, off offset:576
	v_lshl_add_u64 v[42:43], v[42:43], 0, s[34:35]
	global_store_dword v[42:43], v39, off offset:576
	v_lshl_add_u64 v[38:39], v[42:43], 0, s[28:29]
	global_store_dword v[38:39], v35, off offset:576
	v_lshl_add_u64 v[34:35], v[38:39], 0, s[34:35]
	global_store_dword v[34:35], v40, off offset:576
	v_lshl_add_u64 v[34:35], v[34:35], 0, s[28:29]
	global_store_dword v[34:35], v36, off offset:576
	v_lshl_add_u64 v[34:35], v[34:35], 0, s[34:35]
	global_store_dword v[34:35], v41, off offset:576
	v_lshl_add_u64 v[34:35], v[34:35], 0, s[28:29]
	global_store_dword v[34:35], v37, off offset:576
.LBB0_381:
	v_add_u32_e32 v36, 0xa0, v144
	v_mov_b64_e32 v[34:35], s[12:13]
	v_mad_i64_i32 v[34:35], s[58:59], v36, s68, v[34:35]
	v_lshl_add_u64 v[34:35], s[36:37], 1, v[34:35]
	v_lshl_add_u64 v[34:35], v[34:35], 0, v[0:1]
	s_and_b64 vcc, exec, s[8:9]
	v_cvt_pk_bf16_f32 v36, v30, v31
	v_cvt_pk_bf16_f32 v37, v32, v33
	v_cvt_pk_bf16_f32 v38, v26, v27
	v_cvt_pk_bf16_f32 v39, v28, v29
	global_store_dwordx4 v[34:35], v[36:39], off sc1
	s_cbranch_vccnz .LBB0_383
	s_nop 0
	v_mad_u64_u32 v[36:37], s[58:59], v151, s16, 0
	v_mov_b32_e32 v38, v37
	v_mad_u64_u32 v[38:39], s[58:59], v150, s16, v[38:39]
	v_mov_b32_e32 v37, v38
	v_lshl_add_u64 v[36:37], v[36:37], 2, s[14:15]
	v_lshl_add_u64 v[36:37], v[144:145], 2, v[36:37]
	global_store_dword v[36:37], v30, off offset:640
	v_lshl_add_u64 v[36:37], v[36:37], 0, s[28:29]
	global_store_dword v[36:37], v26, off offset:640
	v_lshl_add_u64 v[36:37], v[36:37], 0, s[34:35]
	global_store_dword v[36:37], v31, off offset:640
	v_lshl_add_u64 v[30:31], v[36:37], 0, s[28:29]
	global_store_dword v[30:31], v27, off offset:640
	v_lshl_add_u64 v[26:27], v[30:31], 0, s[34:35]
	global_store_dword v[26:27], v32, off offset:640
	v_lshl_add_u64 v[26:27], v[26:27], 0, s[28:29]
	global_store_dword v[26:27], v28, off offset:640
	v_lshl_add_u64 v[26:27], v[26:27], 0, s[34:35]
	global_store_dword v[26:27], v33, off offset:640
	v_lshl_add_u64 v[26:27], v[26:27], 0, s[28:29]
	global_store_dword v[26:27], v29, off offset:640
.LBB0_383:
	s_and_b64 vcc, exec, s[8:9]
	v_cvt_pk_bf16_f32 v26, v22, v23
	v_cvt_pk_bf16_f32 v27, v24, v25
	v_cvt_pk_bf16_f32 v28, v18, v19
	v_cvt_pk_bf16_f32 v29, v20, v21
	global_store_dwordx4 v[34:35], v[26:29], off offset:256 sc1
	s_cbranch_vccnz .LBB0_385
	s_nop 0
	v_mad_u64_u32 v[26:27], s[58:59], v122, s16, 0
	v_mov_b32_e32 v28, v27
	v_mad_u64_u32 v[28:29], s[58:59], v150, s16, v[28:29]
	v_mov_b32_e32 v27, v28
	v_lshl_add_u64 v[26:27], v[26:27], 2, s[14:15]
	v_lshl_add_u64 v[26:27], v[144:145], 2, v[26:27]
	global_store_dword v[26:27], v22, off offset:640
	v_lshl_add_u64 v[26:27], v[26:27], 0, s[28:29]
	global_store_dword v[26:27], v18, off offset:640
	v_lshl_add_u64 v[26:27], v[26:27], 0, s[34:35]
	global_store_dword v[26:27], v23, off offset:640
	v_lshl_add_u64 v[22:23], v[26:27], 0, s[28:29]
	global_store_dword v[22:23], v19, off offset:640
	v_lshl_add_u64 v[18:19], v[22:23], 0, s[34:35]
	global_store_dword v[18:19], v24, off offset:640
	v_lshl_add_u64 v[18:19], v[18:19], 0, s[28:29]
	global_store_dword v[18:19], v20, off offset:640
	v_lshl_add_u64 v[18:19], v[18:19], 0, s[34:35]
	global_store_dword v[18:19], v25, off offset:640
	v_lshl_add_u64 v[18:19], v[18:19], 0, s[28:29]
	global_store_dword v[18:19], v21, off offset:640
.LBB0_385:
	v_add_u32_e32 v20, 0xb0, v144
	v_mov_b64_e32 v[18:19], s[12:13]
	v_mad_i64_i32 v[18:19], s[58:59], v20, s68, v[18:19]
	v_lshl_add_u64 v[18:19], s[36:37], 1, v[18:19]
	v_lshl_add_u64 v[18:19], v[18:19], 0, v[0:1]
	s_and_b64 vcc, exec, s[8:9]
	v_cvt_pk_bf16_f32 v20, v14, v15
	v_cvt_pk_bf16_f32 v21, v16, v17
	v_cvt_pk_bf16_f32 v22, v10, v11
	v_cvt_pk_bf16_f32 v23, v12, v13
	global_store_dwordx4 v[18:19], v[20:23], off sc1
	s_cbranch_vccnz .LBB0_387
	s_nop 0
	v_mad_u64_u32 v[20:21], s[36:37], v151, s16, 0
	v_mov_b32_e32 v22, v21
	v_mad_u64_u32 v[22:23], s[36:37], v150, s16, v[22:23]
	v_mov_b32_e32 v21, v22
	v_lshl_add_u64 v[20:21], v[20:21], 2, s[14:15]
	v_lshl_add_u64 v[20:21], v[144:145], 2, v[20:21]
	global_store_dword v[20:21], v14, off offset:704
	v_lshl_add_u64 v[20:21], v[20:21], 0, s[28:29]
	global_store_dword v[20:21], v10, off offset:704
	v_lshl_add_u64 v[20:21], v[20:21], 0, s[34:35]
	global_store_dword v[20:21], v15, off offset:704
	v_lshl_add_u64 v[14:15], v[20:21], 0, s[28:29]
	global_store_dword v[14:15], v11, off offset:704
	v_lshl_add_u64 v[10:11], v[14:15], 0, s[34:35]
	global_store_dword v[10:11], v16, off offset:704
	v_lshl_add_u64 v[10:11], v[10:11], 0, s[28:29]
	global_store_dword v[10:11], v12, off offset:704
	v_lshl_add_u64 v[10:11], v[10:11], 0, s[34:35]
	global_store_dword v[10:11], v17, off offset:704
	v_lshl_add_u64 v[10:11], v[10:11], 0, s[28:29]
	global_store_dword v[10:11], v13, off offset:704
.LBB0_387:
	s_and_b64 vcc, exec, s[8:9]
	v_cvt_pk_bf16_f32 v10, v6, v7
	v_cvt_pk_bf16_f32 v11, v8, v9
	v_cvt_pk_bf16_f32 v12, v2, v3
	v_cvt_pk_bf16_f32 v13, v4, v5
	global_store_dwordx4 v[18:19], v[10:13], off offset:256 sc1
	s_cbranch_vccnz .LBB0_389
	s_nop 0
	v_mad_u64_u32 v[10:11], s[8:9], v122, s16, 0
	v_mov_b32_e32 v12, v11
	v_mad_u64_u32 v[12:13], s[8:9], v150, s16, v[12:13]
	v_mov_b32_e32 v11, v12
	v_lshl_add_u64 v[10:11], v[10:11], 2, s[14:15]
	v_lshl_add_u64 v[10:11], v[144:145], 2, v[10:11]
	global_store_dword v[10:11], v6, off offset:704
	v_lshl_add_u64 v[10:11], v[10:11], 0, s[28:29]
	global_store_dword v[10:11], v2, off offset:704
	v_lshl_add_u64 v[10:11], v[10:11], 0, s[34:35]
	global_store_dword v[10:11], v7, off offset:704
	v_lshl_add_u64 v[6:7], v[10:11], 0, s[28:29]
	global_store_dword v[6:7], v3, off offset:704
	v_lshl_add_u64 v[2:3], v[6:7], 0, s[34:35]
	global_store_dword v[2:3], v8, off offset:704
	v_lshl_add_u64 v[2:3], v[2:3], 0, s[28:29]
	global_store_dword v[2:3], v4, off offset:704
	v_lshl_add_u64 v[2:3], v[2:3], 0, s[34:35]
	global_store_dword v[2:3], v9, off offset:704
	v_lshl_add_u64 v[2:3], v[2:3], 0, s[28:29]
	global_store_dword v[2:3], v5, off offset:704

.LBB0_443:
	s_lshl_b64 s[36:37], s[36:37], 2
	s_add_u32 s36, s83, s36
	v_lshl_or_b32 v156, s55, 8, v148
	s_addc_u32 s37, s86, s37
	v_ashrrev_i32_e32 v157, 31, v156
	v_lshl_add_u64 v[136:137], v[156:157], 2, s[36:37]
	global_load_dwordx4 v[138:141], v[136:137], off
	v_lshl_add_u32 v154, s19, 8, v146
	v_ashrrev_i32_e32 v155, 31, v154
	s_mov_b32 s19, s18
	s_mov_b64 s[36:37], 0x80000
	s_and_b64 vcc, exec, s[6:7]
	s_waitcnt vmcnt(0)
	v_pk_mul_f32 v[142:143], s[28:29], v[138:139]
	v_lshlrev_b64 v[138:139], 10, v[154:155]
	v_lshl_add_u64 v[138:139], v[138:139], 0, v[156:157]
	v_lshlrev_b64 v[144:145], 2, v[138:139]
	v_lshl_add_u64 v[138:139], s[34:35], 0, v[144:145]
	global_load_dwordx4 v[150:153], v[138:139], off
	v_pk_mul_f32 v[140:141], s[18:19], v[140:141]
	s_waitcnt vmcnt(0)
	v_pk_fma_f32 v[150:151], v[126:127], v[142:143], v[150:151]
	v_pk_fma_f32 v[152:153], v[128:129], v[140:141], v[152:153]
	v_or_b32_e32 v128, 16, v154
	v_ashrrev_i32_e32 v129, 31, v128
	v_lshlrev_b64 v[128:129], 10, v[128:129]
	v_lshl_add_u64 v[128:129], v[128:129], 0, v[156:157]
	v_lshl_add_u64 v[126:127], s[24:25], 0, v[144:145]
	v_lshlrev_b64 v[158:159], 2, v[128:129]
	global_store_dwordx4 v[126:127], v[150:153], off sc1
	v_lshl_add_u64 v[128:129], s[34:35], 0, v[158:159]
	global_load_dwordx4 v[150:153], v[128:129], off
	s_waitcnt vmcnt(0)
	v_pk_fma_f32 v[152:153], v[124:125], v[140:141], v[152:153]
	v_or_b32_e32 v124, 32, v154
	v_ashrrev_i32_e32 v125, 31, v124
	v_lshlrev_b64 v[124:125], 10, v[124:125]
	v_lshl_add_u64 v[124:125], v[124:125], 0, v[156:157]
	v_pk_fma_f32 v[150:151], v[122:123], v[142:143], v[150:151]
	v_lshl_add_u64 v[122:123], s[24:25], 0, v[158:159]
	v_lshlrev_b64 v[158:159], 2, v[124:125]
	global_store_dwordx4 v[122:123], v[150:153], off sc1
	v_lshl_add_u64 v[124:125], s[34:35], 0, v[158:159]
	global_load_dwordx4 v[150:153], v[124:125], off
	s_waitcnt vmcnt(0)
	v_pk_fma_f32 v[152:153], v[120:121], v[140:141], v[152:153]
	v_or_b32_e32 v120, 48, v154
	v_ashrrev_i32_e32 v121, 31, v120
	v_lshlrev_b64 v[120:121], 10, v[120:121]
	v_lshl_add_u64 v[120:121], v[120:121], 0, v[156:157]
	v_pk_fma_f32 v[150:151], v[118:119], v[142:143], v[150:151]
	v_lshl_add_u64 v[118:119], s[24:25], 0, v[158:159]
	v_lshlrev_b64 v[154:155], 2, v[120:121]
	global_store_dwordx4 v[118:119], v[150:153], off sc1
	v_lshl_add_u64 v[120:121], s[34:35], 0, v[154:155]
	global_load_dwordx4 v[150:153], v[120:121], off
	s_waitcnt vmcnt(0)
	v_pk_fma_f32 v[152:153], v[116:117], v[140:141], v[152:153]
	v_pk_fma_f32 v[150:151], v[114:115], v[142:143], v[150:151]
	v_lshl_add_u64 v[114:115], s[24:25], 0, v[154:155]
	v_lshl_add_u64 v[154:155], v[144:145], 0, s[36:37]
	global_store_dwordx4 v[114:115], v[150:153], off sc1
	v_lshl_add_u64 v[116:117], s[34:35], 0, v[154:155]
	global_load_dwordx4 v[150:153], v[116:117], off
	s_mov_b64 s[36:37], 0x90000
	s_waitcnt vmcnt(0)
	v_pk_fma_f32 v[152:153], v[112:113], v[140:141], v[152:153]
	v_pk_fma_f32 v[150:151], v[110:111], v[142:143], v[150:151]
	v_lshl_add_u64 v[110:111], s[24:25], 0, v[154:155]
	v_lshl_add_u64 v[154:155], v[144:145], 0, s[36:37]
	global_store_dwordx4 v[110:111], v[150:153], off sc1
	v_lshl_add_u64 v[112:113], s[34:35], 0, v[154:155]
	global_load_dwordx4 v[150:153], v[112:113], off
	s_mov_b64 s[36:37], 0xa0000
	s_waitcnt vmcnt(0)
	v_pk_fma_f32 v[152:153], v[108:109], v[140:141], v[152:153]
	v_pk_fma_f32 v[150:151], v[106:107], v[142:143], v[150:151]
	v_lshl_add_u64 v[106:107], s[24:25], 0, v[154:155]
	v_lshl_add_u64 v[154:155], v[144:145], 0, s[36:37]
	global_store_dwordx4 v[106:107], v[150:153], off sc1
	v_lshl_add_u64 v[108:109], s[34:35], 0, v[154:155]
	global_load_dwordx4 v[150:153], v[108:109], off
	s_mov_b64 s[36:37], 0xb0000
	s_waitcnt vmcnt(0)
	v_pk_fma_f32 v[152:153], v[104:105], v[140:141], v[152:153]
	v_pk_fma_f32 v[150:151], v[102:103], v[142:143], v[150:151]
	v_lshl_add_u64 v[102:103], s[24:25], 0, v[154:155]
	v_lshl_add_u64 v[154:155], v[144:145], 0, s[36:37]
	global_store_dwordx4 v[102:103], v[150:153], off sc1
	v_lshl_add_u64 v[104:105], s[34:35], 0, v[154:155]
	global_load_dwordx4 v[150:153], v[104:105], off
	s_mov_b64 s[34:35], -1
	s_waitcnt vmcnt(0)
	v_pk_fma_f32 v[144:145], v[92:93], v[140:141], v[152:153]
	v_pk_fma_f32 v[142:143], v[90:91], v[142:143], v[150:151]
	v_lshl_add_u64 v[90:91], s[24:25], 0, v[154:155]
	global_store_dwordx4 v[90:91], v[142:145], off sc1
	global_load_dwordx4 v[140:143], v[136:137], off offset:64
	s_waitcnt vmcnt(0)
	v_pk_mul_f32 v[150:151], s[28:29], v[140:141]
	v_pk_mul_f32 v[144:145], s[18:19], v[142:143]
	global_load_dwordx4 v[140:143], v[138:139], off offset:64
	s_waitcnt vmcnt(0)
	v_pk_fma_f32 v[100:101], v[100:101], v[144:145], v[142:143]
	v_pk_fma_f32 v[98:99], v[98:99], v[150:151], v[140:141]
	global_store_dwordx4 v[126:127], v[98:101], off offset:64 sc1
	global_load_dwordx4 v[98:101], v[128:129], off offset:64
	s_waitcnt vmcnt(0)
	v_pk_fma_f32 v[96:97], v[96:97], v[144:145], v[100:101]
	v_pk_fma_f32 v[94:95], v[94:95], v[150:151], v[98:99]
	global_store_dwordx4 v[122:123], v[94:97], off offset:64 sc1
	global_load_dwordx4 v[92:95], v[124:125], off offset:64
	s_waitcnt vmcnt(0)
	v_pk_fma_f32 v[88:89], v[88:89], v[144:145], v[94:95]
	v_pk_fma_f32 v[86:87], v[86:87], v[150:151], v[92:93]
	global_store_dwordx4 v[118:119], v[86:89], off offset:64 sc1
	global_load_dwordx4 v[86:89], v[120:121], off offset:64
	s_waitcnt vmcnt(0)
	v_pk_fma_f32 v[84:85], v[84:85], v[144:145], v[88:89]
	v_pk_fma_f32 v[82:83], v[82:83], v[150:151], v[86:87]
	global_store_dwordx4 v[114:115], v[82:85], off offset:64 sc1
	global_load_dwordx4 v[82:85], v[116:117], off offset:64
	s_waitcnt vmcnt(0)
	v_pk_fma_f32 v[80:81], v[80:81], v[144:145], v[84:85]
	v_pk_fma_f32 v[78:79], v[78:79], v[150:151], v[82:83]
	global_store_dwordx4 v[110:111], v[78:81], off offset:64 sc1
	global_load_dwordx4 v[78:81], v[112:113], off offset:64
	s_waitcnt vmcnt(0)
	v_pk_fma_f32 v[76:77], v[76:77], v[144:145], v[80:81]
	v_pk_fma_f32 v[74:75], v[74:75], v[150:151], v[78:79]
	global_store_dwordx4 v[106:107], v[74:77], off offset:64 sc1
	global_load_dwordx4 v[74:77], v[108:109], off offset:64
	s_waitcnt vmcnt(0)
	v_pk_fma_f32 v[68:69], v[68:69], v[144:145], v[76:77]
	v_pk_fma_f32 v[66:67], v[66:67], v[150:151], v[74:75]
	global_store_dwordx4 v[102:103], v[66:69], off offset:64 sc1
	global_load_dwordx4 v[66:69], v[104:105], off offset:64
	s_waitcnt vmcnt(0)
	v_pk_fma_f32 v[60:61], v[60:61], v[144:145], v[68:69]
	v_pk_fma_f32 v[58:59], v[58:59], v[150:151], v[66:67]
	global_store_dwordx4 v[90:91], v[58:61], off offset:64 sc1
	global_load_dwordx4 v[58:61], v[136:137], off offset:512
	s_waitcnt vmcnt(0)
	v_pk_mul_f32 v[66:67], s[18:19], v[60:61]
	v_pk_mul_f32 v[68:69], s[28:29], v[58:59]
	global_load_dwordx4 v[58:61], v[138:139], off offset:512
	s_waitcnt vmcnt(0)
	v_pk_fma_f32 v[60:61], v[72:73], v[66:67], v[60:61]
	v_pk_fma_f32 v[58:59], v[70:71], v[68:69], v[58:59]
	global_store_dwordx4 v[126:127], v[58:61], off offset:512 sc1
	global_load_dwordx4 v[58:61], v[128:129], off offset:512
	s_waitcnt vmcnt(0)
	v_pk_fma_f32 v[60:61], v[64:65], v[66:67], v[60:61]
	v_pk_fma_f32 v[58:59], v[62:63], v[68:69], v[58:59]
	global_store_dwordx4 v[122:123], v[58:61], off offset:512 sc1
	global_load_dwordx4 v[58:61], v[124:125], off offset:512
	s_waitcnt vmcnt(0)
	v_pk_fma_f32 v[56:57], v[56:57], v[66:67], v[60:61]
	v_pk_fma_f32 v[54:55], v[54:55], v[68:69], v[58:59]
	global_store_dwordx4 v[118:119], v[54:57], off offset:512 sc1
	global_load_dwordx4 v[54:57], v[120:121], off offset:512
	s_waitcnt vmcnt(0)
	v_pk_fma_f32 v[52:53], v[52:53], v[66:67], v[56:57]
	v_pk_fma_f32 v[50:51], v[50:51], v[68:69], v[54:55]
	global_store_dwordx4 v[114:115], v[50:53], off offset:512 sc1
	global_load_dwordx4 v[50:53], v[116:117], off offset:512
	s_waitcnt vmcnt(0)
	v_pk_fma_f32 v[48:49], v[48:49], v[66:67], v[52:53]
	v_pk_fma_f32 v[46:47], v[46:47], v[68:69], v[50:51]
	global_store_dwordx4 v[110:111], v[46:49], off offset:512 sc1
	global_load_dwordx4 v[46:49], v[112:113], off offset:512
	s_waitcnt vmcnt(0)
	v_pk_fma_f32 v[40:41], v[40:41], v[66:67], v[48:49]
	v_pk_fma_f32 v[38:39], v[38:39], v[68:69], v[46:47]
	global_store_dwordx4 v[106:107], v[38:41], off offset:512 sc1
	global_load_dwordx4 v[38:41], v[108:109], off offset:512
	s_waitcnt vmcnt(0)
	v_pk_fma_f32 v[32:33], v[32:33], v[66:67], v[40:41]
	v_pk_fma_f32 v[30:31], v[30:31], v[68:69], v[38:39]
	global_store_dwordx4 v[102:103], v[30:33], off offset:512 sc1
	global_load_dwordx4 v[30:33], v[104:105], off offset:512
	s_waitcnt vmcnt(0)
	v_pk_fma_f32 v[24:25], v[24:25], v[66:67], v[32:33]
	v_pk_fma_f32 v[22:23], v[22:23], v[68:69], v[30:31]
	global_store_dwordx4 v[90:91], v[22:25], off offset:512 sc1
	global_load_dwordx4 v[22:25], v[136:137], off offset:576
	s_waitcnt vmcnt(0)
	v_pk_mul_f32 v[30:31], s[18:19], v[24:25]
	v_pk_mul_f32 v[32:33], s[28:29], v[22:23]
	global_load_dwordx4 v[22:25], v[138:139], off offset:576
	s_waitcnt vmcnt(0)
	v_pk_fma_f32 v[24:25], v[44:45], v[30:31], v[24:25]
	v_pk_fma_f32 v[22:23], v[42:43], v[32:33], v[22:23]
	global_store_dwordx4 v[126:127], v[22:25], off offset:576 sc1
	global_load_dwordx4 v[22:25], v[128:129], off offset:576
	s_waitcnt vmcnt(0)
	v_pk_fma_f32 v[24:25], v[36:37], v[30:31], v[24:25]
	v_pk_fma_f32 v[22:23], v[34:35], v[32:33], v[22:23]
	global_store_dwordx4 v[122:123], v[22:25], off offset:576 sc1
	global_load_dwordx4 v[22:25], v[124:125], off offset:576
	s_waitcnt vmcnt(0)
	v_pk_fma_f32 v[24:25], v[28:29], v[30:31], v[24:25]
	v_pk_fma_f32 v[22:23], v[26:27], v[32:33], v[22:23]
	global_store_dwordx4 v[118:119], v[22:25], off offset:576 sc1
	global_load_dwordx4 v[22:25], v[120:121], off offset:576
	s_waitcnt vmcnt(0)
	v_pk_fma_f32 v[20:21], v[20:21], v[30:31], v[24:25]
	v_pk_fma_f32 v[18:19], v[18:19], v[32:33], v[22:23]
	global_store_dwordx4 v[114:115], v[18:21], off offset:576 sc1
	global_load_dwordx4 v[18:21], v[116:117], off offset:576
	s_waitcnt vmcnt(0)
	v_pk_fma_f32 v[16:17], v[16:17], v[30:31], v[20:21]
	v_pk_fma_f32 v[14:15], v[14:15], v[32:33], v[18:19]
	global_store_dwordx4 v[110:111], v[14:17], off offset:576 sc1
	global_load_dwordx4 v[14:17], v[112:113], off offset:576
	s_waitcnt vmcnt(0)
	v_pk_fma_f32 v[12:13], v[12:13], v[30:31], v[16:17]
	v_pk_fma_f32 v[10:11], v[10:11], v[32:33], v[14:15]
	global_store_dwordx4 v[106:107], v[10:13], off offset:576 sc1
	global_load_dwordx4 v[10:13], v[108:109], off offset:576
	s_waitcnt vmcnt(0)
	v_pk_fma_f32 v[8:9], v[8:9], v[30:31], v[12:13]
	v_pk_fma_f32 v[6:7], v[6:7], v[32:33], v[10:11]
	global_store_dwordx4 v[102:103], v[6:9], off offset:576 sc1
	global_load_dwordx4 v[6:9], v[104:105], off offset:576
	s_waitcnt vmcnt(0)
	v_pk_fma_f32 v[4:5], v[4:5], v[30:31], v[8:9]
	v_pk_fma_f32 v[2:3], v[2:3], v[32:33], v[6:7]
	global_store_dwordx4 v[90:91], v[2:5], off offset:576 sc1
	s_cbranch_vccnz .LBB0_426
	s_andn2_b64 vcc, exec, s[4:5]
	s_cbranch_vccnz .LBB0_425
	s_barrier
	s_branch .LBB0_425

.LBB0_494:
	s_mov_b32 s19, s18
	s_cmp_lg_u64 s[36:37], 0
	v_pk_mul_f32 v[140:141], s[18:19], v[140:141]
	v_pk_mul_f32 v[186:187], s[28:29], v[138:139]
	v_pk_mul_f32 v[184:185], s[18:19], v[132:133]
	v_pk_mul_f32 v[148:149], s[28:29], v[130:131]
	s_cselect_b64 s[10:11], -1, 0
	s_cmp_eq_u64 s[36:37], 0
	v_pk_fma_f32 v[130:131], v[126:127], v[186:187], v[142:143]
	v_pk_fma_f32 v[138:139], v[128:129], v[140:141], v[144:145]
	v_pk_fma_f32 v[132:133], v[122:123], v[148:149], v[134:135]
	v_pk_fma_f32 v[134:135], v[124:125], v[184:185], v[136:137]
	s_cbranch_scc1 .LBB0_496
	v_cvt_pk_f16_f32 v122, v130, v131
	v_cvt_pk_f16_f32 v123, v138, v139
	v_cvt_pk_f16_f32 v124, v132, v133
	v_cvt_pk_f16_f32 v125, v134, v135
	global_store_dwordx4 v[156:157], v[122:125], off sc1

.LBB0_500:
	v_cndmask_b32_e64 v0, 0, 1, s[10:11]
	v_pk_fma_f32 v[128:129], v[120:121], v[140:141], v[128:129]
	v_pk_fma_f32 v[126:127], v[118:119], v[186:187], v[126:127]
	v_pk_fma_f32 v[124:125], v[116:117], v[184:185], v[124:125]
	v_cmp_ne_u32_e64 s[6:7], 1, v0
	s_andn2_b64 vcc, exec, s[10:11]
	v_pk_fma_f32 v[122:123], v[114:115], v[148:149], v[122:123]
	s_cbranch_vccnz .LBB0_502
	v_cvt_pk_f16_f32 v114, v126, v127
	v_cvt_pk_f16_f32 v115, v128, v129
	v_cvt_pk_f16_f32 v116, v122, v123
	v_cvt_pk_f16_f32 v117, v124, v125
	global_store_dwordx4 v[136:137], v[114:117], off sc1

.LBB0_506:
	v_pk_fma_f32 v[120:121], v[112:113], v[140:141], v[120:121]
	v_pk_fma_f32 v[118:119], v[110:111], v[186:187], v[118:119]
	v_pk_fma_f32 v[116:117], v[108:109], v[184:185], v[116:117]
	s_and_b64 vcc, exec, s[6:7]
	v_pk_fma_f32 v[114:115], v[106:107], v[148:149], v[114:115]
	s_cbranch_vccnz .LBB0_508
	v_cvt_pk_f16_f32 v106, v118, v119
	v_cvt_pk_f16_f32 v107, v120, v121
	v_cvt_pk_f16_f32 v108, v114, v115
	v_cvt_pk_f16_f32 v109, v116, v117
	global_store_dwordx4 v[136:137], v[106:109], off sc1

.LBB0_512:
	v_pk_fma_f32 v[112:113], v[104:105], v[140:141], v[112:113]
	v_pk_fma_f32 v[110:111], v[102:103], v[186:187], v[110:111]
	v_pk_fma_f32 v[108:109], v[100:101], v[184:185], v[108:109]
	s_and_b64 vcc, exec, s[6:7]
	v_pk_fma_f32 v[106:107], v[98:99], v[148:149], v[106:107]
	s_cbranch_vccnz .LBB0_514
	v_cvt_pk_f16_f32 v98, v110, v111
	v_cvt_pk_f16_f32 v99, v112, v113
	v_cvt_pk_f16_f32 v100, v106, v107
	v_cvt_pk_f16_f32 v101, v108, v109
	global_store_dwordx4 v[136:137], v[98:101], off sc1

.LBB0_518:
	v_pk_fma_f32 v[104:105], v[96:97], v[140:141], v[104:105]
	v_pk_fma_f32 v[102:103], v[94:95], v[186:187], v[102:103]
	v_pk_fma_f32 v[100:101], v[92:93], v[184:185], v[100:101]
	s_and_b64 vcc, exec, s[6:7]
	v_pk_fma_f32 v[98:99], v[90:91], v[148:149], v[98:99]
	s_cbranch_vccnz .LBB0_520
	v_cvt_pk_f16_f32 v90, v102, v103
	v_cvt_pk_f16_f32 v91, v104, v105
	v_cvt_pk_f16_f32 v92, v98, v99
	v_cvt_pk_f16_f32 v93, v100, v101
	global_store_dwordx4 v[136:137], v[90:93], off sc1

.LBB0_524:
	v_pk_fma_f32 v[96:97], v[88:89], v[140:141], v[96:97]
	v_pk_fma_f32 v[94:95], v[86:87], v[186:187], v[94:95]
	v_pk_fma_f32 v[92:93], v[84:85], v[184:185], v[92:93]
	s_and_b64 vcc, exec, s[6:7]
	v_pk_fma_f32 v[90:91], v[82:83], v[148:149], v[90:91]
	s_cbranch_vccnz .LBB0_526
	v_cvt_pk_f16_f32 v82, v94, v95
	v_cvt_pk_f16_f32 v83, v96, v97
	v_cvt_pk_f16_f32 v84, v90, v91
	v_cvt_pk_f16_f32 v85, v92, v93
	global_store_dwordx4 v[136:137], v[82:85], off sc1

.LBB0_530:
	v_pk_fma_f32 v[88:89], v[80:81], v[140:141], v[88:89]
	v_pk_fma_f32 v[86:87], v[78:79], v[186:187], v[86:87]
	v_pk_fma_f32 v[84:85], v[76:77], v[184:185], v[84:85]
	s_and_b64 vcc, exec, s[6:7]
	v_pk_fma_f32 v[136:137], v[74:75], v[148:149], v[82:83]
	s_cbranch_vccnz .LBB0_532
	v_cvt_pk_f16_f32 v74, v86, v87
	v_cvt_pk_f16_f32 v75, v88, v89
	v_cvt_pk_f16_f32 v76, v136, v137
	v_cvt_pk_f16_f32 v77, v84, v85
	global_store_dwordx4 v[142:143], v[74:77], off sc1

.LBB0_536:
	v_pk_fma_f32 v[140:141], v[72:73], v[140:141], v[80:81]
	v_pk_fma_f32 v[144:145], v[70:71], v[186:187], v[78:79]
	v_pk_fma_f32 v[142:143], v[68:69], v[184:185], v[76:77]
	s_and_b64 vcc, exec, s[6:7]
	v_pk_fma_f32 v[148:149], v[66:67], v[148:149], v[74:75]
	s_cbranch_vccnz .LBB0_538
	v_cvt_pk_f16_f32 v66, v144, v145
	v_cvt_pk_f16_f32 v67, v140, v141
	v_cvt_pk_f16_f32 v68, v148, v149
	v_cvt_pk_f16_f32 v69, v142, v143
	global_store_dwordx4 v[82:83], v[66:69], off sc1

.LBB0_542:
	s_mov_b32 s19, s18
	v_pk_mul_f32 v[150:151], s[18:19], v[80:81]
	v_pk_mul_f32 v[154:155], s[28:29], v[78:79]
	v_pk_mul_f32 v[152:153], s[18:19], v[72:73]
	v_pk_mul_f32 v[184:185], s[28:29], v[70:71]
	v_pk_fma_f32 v[70:71], v[62:63], v[154:155], v[74:75]
	v_pk_fma_f32 v[72:73], v[64:65], v[150:151], v[76:77]
	v_pk_fma_f32 v[66:67], v[58:59], v[184:185], v[66:67]
	s_and_b64 vcc, exec, s[6:7]
	v_pk_fma_f32 v[68:69], v[60:61], v[152:153], v[68:69]
	s_cbranch_vccnz .LBB0_544
	v_cvt_pk_f16_f32 v58, v70, v71
	v_cvt_pk_f16_f32 v59, v72, v73
	v_cvt_pk_f16_f32 v60, v66, v67
	v_cvt_pk_f16_f32 v61, v68, v69
	global_store_dwordx4 v[186:187], v[58:61], off sc1

.LBB0_548:
	v_pk_fma_f32 v[64:65], v[56:57], v[150:151], v[64:65]
	v_pk_fma_f32 v[62:63], v[54:55], v[154:155], v[62:63]
	v_pk_fma_f32 v[60:61], v[52:53], v[152:153], v[60:61]
	s_and_b64 vcc, exec, s[6:7]
	v_pk_fma_f32 v[58:59], v[50:51], v[184:185], v[58:59]
	s_cbranch_vccnz .LBB0_550
	v_cvt_pk_f16_f32 v50, v62, v63
	v_cvt_pk_f16_f32 v51, v64, v65
	v_cvt_pk_f16_f32 v52, v58, v59
	v_cvt_pk_f16_f32 v53, v60, v61
	global_store_dwordx4 v[74:75], v[50:53], off sc1

.LBB0_554:
	v_pk_fma_f32 v[56:57], v[48:49], v[150:151], v[56:57]
	v_pk_fma_f32 v[54:55], v[46:47], v[154:155], v[54:55]
	v_pk_fma_f32 v[52:53], v[44:45], v[152:153], v[52:53]
	s_and_b64 vcc, exec, s[6:7]
	v_pk_fma_f32 v[50:51], v[42:43], v[184:185], v[50:51]
	s_cbranch_vccnz .LBB0_556
	v_cvt_pk_f16_f32 v42, v54, v55
	v_cvt_pk_f16_f32 v43, v56, v57
	v_cvt_pk_f16_f32 v44, v50, v51
	v_cvt_pk_f16_f32 v45, v52, v53
	global_store_dwordx4 v[74:75], v[42:45], off sc1

.LBB0_560:
	v_pk_fma_f32 v[48:49], v[40:41], v[150:151], v[48:49]
	v_pk_fma_f32 v[46:47], v[38:39], v[154:155], v[46:47]
	v_pk_fma_f32 v[44:45], v[36:37], v[152:153], v[44:45]
	s_and_b64 vcc, exec, s[6:7]
	v_pk_fma_f32 v[42:43], v[34:35], v[184:185], v[42:43]
	s_cbranch_vccnz .LBB0_562
	v_cvt_pk_f16_f32 v34, v46, v47
	v_cvt_pk_f16_f32 v35, v48, v49
	v_cvt_pk_f16_f32 v36, v42, v43
	v_cvt_pk_f16_f32 v37, v44, v45
	global_store_dwordx4 v[74:75], v[34:37], off sc1

.LBB0_566:
	v_pk_fma_f32 v[40:41], v[32:33], v[150:151], v[40:41]
	v_pk_fma_f32 v[38:39], v[30:31], v[154:155], v[38:39]
	v_pk_fma_f32 v[36:37], v[28:29], v[152:153], v[36:37]
	s_and_b64 vcc, exec, s[6:7]
	v_pk_fma_f32 v[34:35], v[26:27], v[184:185], v[34:35]
	s_cbranch_vccnz .LBB0_568
	v_cvt_pk_f16_f32 v26, v38, v39
	v_cvt_pk_f16_f32 v27, v40, v41
	v_cvt_pk_f16_f32 v28, v34, v35
	v_cvt_pk_f16_f32 v29, v36, v37
	global_store_dwordx4 v[74:75], v[26:29], off sc1

.LBB0_572:
	v_pk_fma_f32 v[32:33], v[24:25], v[150:151], v[32:33]
	v_pk_fma_f32 v[30:31], v[22:23], v[154:155], v[30:31]
	v_pk_fma_f32 v[28:29], v[20:21], v[152:153], v[28:29]
	s_and_b64 vcc, exec, s[6:7]
	v_pk_fma_f32 v[26:27], v[18:19], v[184:185], v[26:27]
	s_cbranch_vccnz .LBB0_574
	v_cvt_pk_f16_f32 v18, v30, v31
	v_cvt_pk_f16_f32 v19, v32, v33
	v_cvt_pk_f16_f32 v20, v26, v27
	v_cvt_pk_f16_f32 v21, v28, v29
	global_store_dwordx4 v[74:75], v[18:21], off sc1

.LBB0_578:
	v_pk_fma_f32 v[74:75], v[16:17], v[150:151], v[24:25]
	v_pk_fma_f32 v[78:79], v[14:15], v[154:155], v[22:23]
	v_pk_fma_f32 v[76:77], v[12:13], v[152:153], v[20:21]
	s_and_b64 vcc, exec, s[6:7]
	v_pk_fma_f32 v[80:81], v[10:11], v[184:185], v[18:19]
	s_cbranch_vccnz .LBB0_580
	v_cvt_pk_f16_f32 v10, v78, v79
	v_cvt_pk_f16_f32 v11, v74, v75
	v_cvt_pk_f16_f32 v12, v80, v81
	v_cvt_pk_f16_f32 v13, v76, v77
	global_store_dwordx4 v[156:157], v[10:13], off sc1

.LBB0_584:
	v_pk_fma_f32 v[150:151], v[8:9], v[150:151], v[16:17]
	v_pk_fma_f32 v[154:155], v[6:7], v[154:155], v[14:15]
	v_pk_fma_f32 v[152:153], v[4:5], v[152:153], v[12:13]
	s_and_b64 vcc, exec, s[6:7]
	v_pk_fma_f32 v[156:157], v[2:3], v[184:185], v[10:11]
	s_cbranch_vccnz .LBB0_586
	v_cvt_pk_f16_f32 v2, v154, v155
	v_cvt_pk_f16_f32 v3, v150, v151
	v_cvt_pk_f16_f32 v4, v156, v157
	v_cvt_pk_f16_f32 v5, v152, v153
	global_store_dwordx4 v[18:19], v[2:5], off sc1

.LBB0_622:
	v_lshl_add_u32 v0, v188, 2, 0
	ds_read_b32 v22, v0 offset:8192
	v_add_u32_e32 v170, s16, v188
	v_ashrrev_i32_e32 v171, 31, v170
	v_lshlrev_b64 v[158:159], 10, v[170:171]
	v_lshl_add_u64 v[172:173], v[158:159], 0, v[146:147]
	s_waitcnt lgkmcnt(0)
	v_pk_mul_f32 v[18:19], v[130:131], v[22:23] op_sel_hi:[1,0]
	v_pk_mul_f32 v[20:21], v[138:139], v[22:23] op_sel_hi:[1,0]
	v_pk_mul_f32 v[130:131], v[132:133], v[22:23] op_sel_hi:[1,0]
	v_pk_mul_f32 v[22:23], v[134:135], v[22:23] op_sel_hi:[1,0]
	s_waitcnt vmcnt(0)
	v_pk_mul_f32 v[20:21], v[8:9], v[20:21]
	v_pk_mul_f32 v[18:19], v[6:7], v[18:19]
	v_pk_mul_f32 v[24:25], v[4:5], v[22:23]
	v_pk_mul_f32 v[22:23], v[2:3], v[130:131]
	s_and_b64 vcc, exec, s[10:11]
	s_cbranch_vccz .LBB0_648
	v_pk_fma_f32 v[132:133], v[168:169], v[20:21], v[16:17]
	v_pk_fma_f32 v[130:131], v[162:163], v[18:19], v[14:15]
	v_pk_fma_f32 v[134:135], v[166:167], v[24:25], v[12:13]
	v_pk_fma_f32 v[138:139], v[164:165], v[22:23], v[10:11]
	v_cvt_pk_bf16_f32 v130, v130, v131
	v_cvt_pk_bf16_f32 v131, v132, v133
	s_nop 0
	v_cvt_pk_bf16_f32 v132, v138, v139
	v_cvt_pk_bf16_f32 v133, v134, v135
	v_lshl_add_u64 v[134:135], v[172:173], 1, s[82:83]
	global_store_dwordx4 v[134:135], v[130:133], off sc1
	s_nop 1
	v_lshl_add_u64 v[132:133], v[172:173], 2, s[24:25]
	s_cbranch_execnz .LBB0_625
.LBB0_624:
	global_store_dwordx4 v[132:133], v[18:21], off sc1
	global_store_dwordx4 v[132:133], v[22:25], off offset:16 sc1
.LBB0_625:
	ds_read_b32 v22, v0 offset:8256
	v_add3_u32 v18, s16, v188, 16
	v_ashrrev_i32_e32 v19, 31, v18
	v_lshlrev_b64 v[130:131], 10, v[18:19]
	v_lshl_add_u64 v[134:135], v[130:131], 0, v[146:147]
	s_waitcnt lgkmcnt(0)
	v_pk_mul_f32 v[18:19], v[128:129], v[22:23] op_sel_hi:[1,0]
	v_pk_mul_f32 v[24:25], v[126:127], v[22:23] op_sel_hi:[1,0]
	v_pk_mul_f32 v[20:21], v[8:9], v[18:19]
	v_pk_mul_f32 v[18:19], v[6:7], v[24:25]
	v_pk_mul_f32 v[24:25], v[124:125], v[22:23] op_sel_hi:[1,0]
	v_pk_mul_f32 v[22:23], v[122:123], v[22:23] op_sel_hi:[1,0]
	v_pk_mul_f32 v[24:25], v[4:5], v[24:25]
	s_and_b64 vcc, exec, s[6:7]
	v_pk_mul_f32 v[22:23], v[2:3], v[22:23]
	s_cbranch_vccnz .LBB0_649
	v_pk_fma_f32 v[124:125], v[168:169], v[20:21], v[16:17]
	v_pk_fma_f32 v[122:123], v[162:163], v[18:19], v[14:15]
	v_pk_fma_f32 v[126:127], v[166:167], v[24:25], v[12:13]
	v_pk_fma_f32 v[128:129], v[164:165], v[22:23], v[10:11]
	v_cvt_pk_bf16_f32 v122, v122, v123
	v_cvt_pk_bf16_f32 v123, v124, v125
	s_nop 0
	v_cvt_pk_bf16_f32 v124, v128, v129
	v_cvt_pk_bf16_f32 v125, v126, v127
	v_lshl_add_u64 v[126:127], v[134:135], 1, s[82:83]
	global_store_dwordx4 v[126:127], v[122:125], off sc1
	s_nop 1
	v_lshl_add_u64 v[124:125], v[134:135], 2, s[24:25]
	s_cbranch_execnz .LBB0_628
.LBB0_627:
	global_store_dwordx4 v[124:125], v[18:21], off sc1
	global_store_dwordx4 v[124:125], v[22:25], off offset:16 sc1
.LBB0_628:
	ds_read_b32 v22, v0 offset:8320
	v_add3_u32 v18, s16, v188, 32
	v_ashrrev_i32_e32 v19, 31, v18
	v_lshlrev_b64 v[122:123], 10, v[18:19]
	v_lshl_add_u64 v[126:127], v[122:123], 0, v[146:147]
	s_waitcnt lgkmcnt(0)
	v_pk_mul_f32 v[18:19], v[120:121], v[22:23] op_sel_hi:[1,0]
	v_pk_mul_f32 v[24:25], v[118:119], v[22:23] op_sel_hi:[1,0]
	v_pk_mul_f32 v[20:21], v[8:9], v[18:19]
	v_pk_mul_f32 v[18:19], v[6:7], v[24:25]
	v_pk_mul_f32 v[24:25], v[116:117], v[22:23] op_sel_hi:[1,0]
	v_pk_mul_f32 v[22:23], v[114:115], v[22:23] op_sel_hi:[1,0]
	v_pk_mul_f32 v[24:25], v[4:5], v[24:25]
	s_and_b64 vcc, exec, s[6:7]
	v_pk_mul_f32 v[22:23], v[2:3], v[22:23]
	s_cbranch_vccnz .LBB0_650
	v_pk_fma_f32 v[116:117], v[168:169], v[20:21], v[16:17]
	v_pk_fma_f32 v[114:115], v[162:163], v[18:19], v[14:15]
	v_pk_fma_f32 v[118:119], v[166:167], v[24:25], v[12:13]
	v_pk_fma_f32 v[120:121], v[164:165], v[22:23], v[10:11]
	v_cvt_pk_bf16_f32 v114, v114, v115
	v_cvt_pk_bf16_f32 v115, v116, v117
	s_nop 0
	v_cvt_pk_bf16_f32 v116, v120, v121
	v_cvt_pk_bf16_f32 v117, v118, v119
	v_lshl_add_u64 v[118:119], v[126:127], 1, s[82:83]
	global_store_dwordx4 v[118:119], v[114:117], off sc1
	s_nop 1
	v_lshl_add_u64 v[116:117], v[126:127], 2, s[24:25]
	s_cbranch_execnz .LBB0_631
.LBB0_630:
	global_store_dwordx4 v[116:117], v[18:21], off sc1
	global_store_dwordx4 v[116:117], v[22:25], off offset:16 sc1
.LBB0_631:
	ds_read_b32 v22, v0 offset:8384
	v_add3_u32 v18, s16, v188, 48
	v_ashrrev_i32_e32 v19, 31, v18
	v_lshlrev_b64 v[114:115], 10, v[18:19]
	v_lshl_add_u64 v[118:119], v[114:115], 0, v[146:147]
	s_waitcnt lgkmcnt(0)
	v_pk_mul_f32 v[18:19], v[112:113], v[22:23] op_sel_hi:[1,0]
	v_pk_mul_f32 v[24:25], v[110:111], v[22:23] op_sel_hi:[1,0]
	v_pk_mul_f32 v[20:21], v[8:9], v[18:19]
	v_pk_mul_f32 v[18:19], v[6:7], v[24:25]
	v_pk_mul_f32 v[24:25], v[108:109], v[22:23] op_sel_hi:[1,0]
	v_pk_mul_f32 v[22:23], v[106:107], v[22:23] op_sel_hi:[1,0]
	v_pk_mul_f32 v[24:25], v[4:5], v[24:25]
	s_and_b64 vcc, exec, s[6:7]
	v_pk_mul_f32 v[22:23], v[2:3], v[22:23]
	s_cbranch_vccnz .LBB0_651
	v_pk_fma_f32 v[108:109], v[168:169], v[20:21], v[16:17]
	v_pk_fma_f32 v[106:107], v[162:163], v[18:19], v[14:15]
	v_pk_fma_f32 v[110:111], v[166:167], v[24:25], v[12:13]
	v_pk_fma_f32 v[112:113], v[164:165], v[22:23], v[10:11]
	v_cvt_pk_bf16_f32 v106, v106, v107
	v_cvt_pk_bf16_f32 v107, v108, v109
	s_nop 0
	v_cvt_pk_bf16_f32 v108, v112, v113
	v_cvt_pk_bf16_f32 v109, v110, v111
	v_lshl_add_u64 v[110:111], v[118:119], 1, s[82:83]
	global_store_dwordx4 v[110:111], v[106:109], off sc1
	s_nop 1
	v_lshl_add_u64 v[108:109], v[118:119], 2, s[24:25]
	s_cbranch_execnz .LBB0_634
.LBB0_633:
	global_store_dwordx4 v[108:109], v[18:21], off sc1
	global_store_dwordx4 v[108:109], v[22:25], off offset:16 sc1
.LBB0_634:
	ds_read_b32 v22, v0 offset:8704
	v_add_u32_e32 v18, 0x80, v170
	v_ashrrev_i32_e32 v19, 31, v18
	v_lshlrev_b64 v[106:107], 10, v[18:19]
	v_lshl_add_u64 v[110:111], v[106:107], 0, v[146:147]
	s_waitcnt lgkmcnt(0)
	v_pk_mul_f32 v[18:19], v[104:105], v[22:23] op_sel_hi:[1,0]
	v_pk_mul_f32 v[24:25], v[102:103], v[22:23] op_sel_hi:[1,0]
	v_pk_mul_f32 v[20:21], v[8:9], v[18:19]
	v_pk_mul_f32 v[18:19], v[6:7], v[24:25]
	v_pk_mul_f32 v[24:25], v[100:101], v[22:23] op_sel_hi:[1,0]
	v_pk_mul_f32 v[22:23], v[98:99], v[22:23] op_sel_hi:[1,0]
	v_pk_mul_f32 v[24:25], v[4:5], v[24:25]
	s_and_b64 vcc, exec, s[6:7]
	v_pk_mul_f32 v[22:23], v[2:3], v[22:23]
	s_cbranch_vccnz .LBB0_652
	v_pk_fma_f32 v[100:101], v[168:169], v[20:21], v[16:17]
	v_pk_fma_f32 v[98:99], v[162:163], v[18:19], v[14:15]
	v_pk_fma_f32 v[102:103], v[166:167], v[24:25], v[12:13]
	v_pk_fma_f32 v[104:105], v[164:165], v[22:23], v[10:11]
	v_cvt_pk_bf16_f32 v98, v98, v99
	v_cvt_pk_bf16_f32 v99, v100, v101
	s_nop 0
	v_cvt_pk_bf16_f32 v100, v104, v105
	v_cvt_pk_bf16_f32 v101, v102, v103
	v_lshl_add_u64 v[102:103], v[110:111], 1, s[82:83]
	global_store_dwordx4 v[102:103], v[98:101], off sc1
	s_nop 1
	v_lshl_add_u64 v[100:101], v[110:111], 2, s[24:25]
	s_cbranch_execnz .LBB0_637
.LBB0_636:
	global_store_dwordx4 v[100:101], v[18:21], off sc1
	global_store_dwordx4 v[100:101], v[22:25], off offset:16 sc1
.LBB0_637:
	ds_read_b32 v22, v0 offset:8768
	v_add_u32_e32 v18, 0x90, v170
	v_ashrrev_i32_e32 v19, 31, v18
	v_lshlrev_b64 v[98:99], 10, v[18:19]
	v_lshl_add_u64 v[102:103], v[98:99], 0, v[146:147]
	s_waitcnt lgkmcnt(0)
	v_pk_mul_f32 v[18:19], v[96:97], v[22:23] op_sel_hi:[1,0]
	v_pk_mul_f32 v[24:25], v[94:95], v[22:23] op_sel_hi:[1,0]
	v_pk_mul_f32 v[20:21], v[8:9], v[18:19]
	v_pk_mul_f32 v[18:19], v[6:7], v[24:25]
	v_pk_mul_f32 v[24:25], v[92:93], v[22:23] op_sel_hi:[1,0]
	v_pk_mul_f32 v[22:23], v[90:91], v[22:23] op_sel_hi:[1,0]
	v_pk_mul_f32 v[24:25], v[4:5], v[24:25]
	s_and_b64 vcc, exec, s[6:7]
	v_pk_mul_f32 v[22:23], v[2:3], v[22:23]
	s_cbranch_vccnz .LBB0_653
	v_pk_fma_f32 v[92:93], v[168:169], v[20:21], v[16:17]
	v_pk_fma_f32 v[90:91], v[162:163], v[18:19], v[14:15]
	v_pk_fma_f32 v[94:95], v[166:167], v[24:25], v[12:13]
	v_pk_fma_f32 v[96:97], v[164:165], v[22:23], v[10:11]
	v_cvt_pk_bf16_f32 v90, v90, v91
	v_cvt_pk_bf16_f32 v91, v92, v93
	s_nop 0
	v_cvt_pk_bf16_f32 v92, v96, v97
	v_cvt_pk_bf16_f32 v93, v94, v95
	v_lshl_add_u64 v[94:95], v[102:103], 1, s[82:83]
	global_store_dwordx4 v[94:95], v[90:93], off sc1
	s_nop 1
	v_lshl_add_u64 v[92:93], v[102:103], 2, s[24:25]
	s_cbranch_execnz .LBB0_640
.LBB0_639:
	global_store_dwordx4 v[92:93], v[18:21], off sc1
	global_store_dwordx4 v[92:93], v[22:25], off offset:16 sc1
.LBB0_640:
	ds_read_b32 v22, v0 offset:8832
	v_add_u32_e32 v18, 0xa0, v170
	v_ashrrev_i32_e32 v19, 31, v18
	v_lshlrev_b64 v[90:91], 10, v[18:19]
	v_lshl_add_u64 v[94:95], v[90:91], 0, v[146:147]
	s_waitcnt lgkmcnt(0)
	v_pk_mul_f32 v[18:19], v[88:89], v[22:23] op_sel_hi:[1,0]
	v_pk_mul_f32 v[24:25], v[86:87], v[22:23] op_sel_hi:[1,0]
	v_pk_mul_f32 v[20:21], v[8:9], v[18:19]
	v_pk_mul_f32 v[18:19], v[6:7], v[24:25]
	v_pk_mul_f32 v[24:25], v[84:85], v[22:23] op_sel_hi:[1,0]
	v_pk_mul_f32 v[22:23], v[136:137], v[22:23] op_sel_hi:[1,0]
	v_pk_mul_f32 v[24:25], v[4:5], v[24:25]
	s_and_b64 vcc, exec, s[6:7]
	v_pk_mul_f32 v[22:23], v[2:3], v[22:23]
	s_cbranch_vccnz .LBB0_654
	v_pk_fma_f32 v[86:87], v[168:169], v[20:21], v[16:17]
	v_pk_fma_f32 v[84:85], v[162:163], v[18:19], v[14:15]
	v_pk_fma_f32 v[88:89], v[166:167], v[24:25], v[12:13]
	v_pk_fma_f32 v[96:97], v[164:165], v[22:23], v[10:11]
	v_cvt_pk_bf16_f32 v84, v84, v85
	v_cvt_pk_bf16_f32 v85, v86, v87
	s_nop 0
	v_cvt_pk_bf16_f32 v86, v96, v97
	v_cvt_pk_bf16_f32 v87, v88, v89
	v_lshl_add_u64 v[88:89], v[94:95], 1, s[82:83]
	global_store_dwordx4 v[88:89], v[84:87], off sc1
	s_nop 1
	v_lshl_add_u64 v[86:87], v[94:95], 2, s[24:25]
	s_cbranch_execnz .LBB0_643
.LBB0_642:
	global_store_dwordx4 v[86:87], v[18:21], off sc1
	global_store_dwordx4 v[86:87], v[22:25], off offset:16 sc1
.LBB0_643:
	ds_read_b32 v20, v0 offset:8896
	v_add_u32_e32 v18, 0xb0, v170
	v_ashrrev_i32_e32 v19, 31, v18
	v_lshlrev_b64 v[84:85], 10, v[18:19]
	v_lshl_add_u64 v[18:19], v[84:85], 0, v[146:147]
	s_waitcnt lgkmcnt(0)
	v_pk_mul_f32 v[22:23], v[140:141], v[20:21] op_sel_hi:[1,0]
	v_pk_mul_f32 v[24:25], v[144:145], v[20:21] op_sel_hi:[1,0]
	v_pk_mul_f32 v[8:9], v[8:9], v[22:23]
	v_pk_mul_f32 v[22:23], v[142:143], v[20:21] op_sel_hi:[1,0]
	v_pk_mul_f32 v[20:21], v[148:149], v[20:21] op_sel_hi:[1,0]
	v_pk_mul_f32 v[6:7], v[6:7], v[24:25]
	v_pk_mul_f32 v[4:5], v[4:5], v[22:23]
	s_and_b64 vcc, exec, s[6:7]
	v_pk_mul_f32 v[2:3], v[2:3], v[20:21]
	s_cbranch_vccnz .LBB0_655
	v_pk_fma_f32 v[14:15], v[162:163], v[6:7], v[14:15]
	v_pk_fma_f32 v[20:21], v[166:167], v[4:5], v[12:13]
	v_pk_fma_f32 v[12:13], v[164:165], v[2:3], v[10:11]
	v_cvt_pk_bf16_f32 v10, v14, v15
	v_lshl_add_u64 v[14:15], v[18:19], 1, s[82:83]
	v_pk_fma_f32 v[16:17], v[168:169], v[8:9], v[16:17]
	s_nop 0
	v_cvt_pk_bf16_f32 v11, v16, v17
	v_cvt_pk_bf16_f32 v12, v12, v13
	v_cvt_pk_bf16_f32 v13, v20, v21
	global_store_dwordx4 v[14:15], v[10:13], off sc1
	v_lshl_add_u64 v[88:89], v[18:19], 2, s[24:25]
	s_cbranch_execnz .LBB0_646
.LBB0_645:
	global_store_dwordx4 v[88:89], v[6:9], off sc1
	global_store_dwordx4 v[88:89], v[2:5], off offset:16 sc1

.LBB0_657:
	ds_read_b32 v18, v0 offset:8192
	s_and_b64 vcc, exec, s[6:7]
	s_waitcnt lgkmcnt(0)
	v_pk_mul_f32 v[20:21], v[72:73], v[18:19] op_sel_hi:[1,0]
	v_pk_mul_f32 v[22:23], v[70:71], v[18:19] op_sel_hi:[1,0]
	v_pk_mul_f32 v[24:25], v[68:69], v[18:19] op_sel_hi:[1,0]
	v_pk_mul_f32 v[66:67], v[66:67], v[18:19] op_sel_hi:[1,0]
	s_waitcnt vmcnt(0)
	v_pk_mul_f32 v[20:21], v[8:9], v[20:21]
	v_pk_mul_f32 v[18:19], v[6:7], v[22:23]
	v_pk_mul_f32 v[24:25], v[4:5], v[24:25]
	v_pk_mul_f32 v[22:23], v[2:3], v[66:67]
	s_cbranch_vccnz .LBB0_876
	v_lshl_add_u64 v[70:71], v[158:159], 0, v[82:83]
	v_pk_fma_f32 v[68:69], v[104:105], v[20:21], v[16:17]
	v_pk_fma_f32 v[66:67], v[94:95], v[18:19], v[14:15]
	v_lshl_add_u64 v[70:71], v[70:71], 1, s[82:83]
	v_pk_fma_f32 v[72:73], v[102:103], v[24:25], v[12:13]
	v_pk_fma_f32 v[110:111], v[96:97], v[22:23], v[10:11]
	v_cvt_pk_bf16_f32 v66, v66, v67
	v_cvt_pk_bf16_f32 v67, v68, v69
	s_nop 0
	v_cvt_pk_bf16_f32 v68, v110, v111
	v_cvt_pk_bf16_f32 v69, v72, v73
	global_store_dwordx4 v[70:71], v[66:69], off sc1
	s_cbranch_execnz .LBB0_660
.LBB0_659:
	global_store_dwordx4 v[132:133], v[18:21], off offset:512 sc1
	global_store_dwordx4 v[132:133], v[22:25], off offset:528 sc1
.LBB0_660:
	ds_read_b32 v18, v0 offset:8256
	s_and_b64 vcc, exec, s[6:7]
	s_waitcnt lgkmcnt(0)
	v_pk_mul_f32 v[20:21], v[64:65], v[18:19] op_sel_hi:[1,0]
	v_pk_mul_f32 v[22:23], v[62:63], v[18:19] op_sel_hi:[1,0]
	v_pk_mul_f32 v[24:25], v[60:61], v[18:19] op_sel_hi:[1,0]
	v_pk_mul_f32 v[58:59], v[58:59], v[18:19] op_sel_hi:[1,0]
	v_pk_mul_f32 v[20:21], v[8:9], v[20:21]
	v_pk_mul_f32 v[18:19], v[6:7], v[22:23]
	v_pk_mul_f32 v[24:25], v[4:5], v[24:25]
	v_pk_mul_f32 v[22:23], v[2:3], v[58:59]
	s_cbranch_vccnz .LBB0_877
	v_lshl_add_u64 v[62:63], v[130:131], 0, v[82:83]
	v_pk_fma_f32 v[60:61], v[104:105], v[20:21], v[16:17]
	v_pk_fma_f32 v[58:59], v[94:95], v[18:19], v[14:15]
	v_lshl_add_u64 v[62:63], v[62:63], 1, s[82:83]
	v_pk_fma_f32 v[64:65], v[102:103], v[24:25], v[12:13]
	v_pk_fma_f32 v[66:67], v[96:97], v[22:23], v[10:11]
	v_cvt_pk_bf16_f32 v58, v58, v59
	v_cvt_pk_bf16_f32 v59, v60, v61
	s_nop 0
	v_cvt_pk_bf16_f32 v60, v66, v67
	v_cvt_pk_bf16_f32 v61, v64, v65
	global_store_dwordx4 v[62:63], v[58:61], off sc1
	s_cbranch_execnz .LBB0_663
.LBB0_662:
	global_store_dwordx4 v[124:125], v[18:21], off offset:512 sc1
	global_store_dwordx4 v[124:125], v[22:25], off offset:528 sc1
.LBB0_663:
	ds_read_b32 v18, v0 offset:8320
	s_and_b64 vcc, exec, s[6:7]
	s_waitcnt lgkmcnt(0)
	v_pk_mul_f32 v[20:21], v[56:57], v[18:19] op_sel_hi:[1,0]
	v_pk_mul_f32 v[22:23], v[54:55], v[18:19] op_sel_hi:[1,0]
	v_pk_mul_f32 v[24:25], v[52:53], v[18:19] op_sel_hi:[1,0]
	v_pk_mul_f32 v[50:51], v[50:51], v[18:19] op_sel_hi:[1,0]
	v_pk_mul_f32 v[20:21], v[8:9], v[20:21]
	v_pk_mul_f32 v[18:19], v[6:7], v[22:23]
	v_pk_mul_f32 v[24:25], v[4:5], v[24:25]
	v_pk_mul_f32 v[22:23], v[2:3], v[50:51]
	s_cbranch_vccnz .LBB0_878
	v_lshl_add_u64 v[54:55], v[122:123], 0, v[82:83]
	v_pk_fma_f32 v[52:53], v[104:105], v[20:21], v[16:17]
	v_pk_fma_f32 v[50:51], v[94:95], v[18:19], v[14:15]
	v_lshl_add_u64 v[54:55], v[54:55], 1, s[82:83]
	v_pk_fma_f32 v[56:57], v[102:103], v[24:25], v[12:13]
	v_pk_fma_f32 v[58:59], v[96:97], v[22:23], v[10:11]
	v_cvt_pk_bf16_f32 v50, v50, v51
	v_cvt_pk_bf16_f32 v51, v52, v53
	s_nop 0
	v_cvt_pk_bf16_f32 v52, v58, v59
	v_cvt_pk_bf16_f32 v53, v56, v57
	global_store_dwordx4 v[54:55], v[50:53], off sc1
	s_cbranch_execnz .LBB0_666
.LBB0_665:
	global_store_dwordx4 v[116:117], v[18:21], off offset:512 sc1
	global_store_dwordx4 v[116:117], v[22:25], off offset:528 sc1
.LBB0_666:
	ds_read_b32 v18, v0 offset:8384
	s_and_b64 vcc, exec, s[6:7]
	s_waitcnt lgkmcnt(0)
	v_pk_mul_f32 v[20:21], v[48:49], v[18:19] op_sel_hi:[1,0]
	v_pk_mul_f32 v[22:23], v[46:47], v[18:19] op_sel_hi:[1,0]
	v_pk_mul_f32 v[24:25], v[44:45], v[18:19] op_sel_hi:[1,0]
	v_pk_mul_f32 v[42:43], v[42:43], v[18:19] op_sel_hi:[1,0]
	v_pk_mul_f32 v[20:21], v[8:9], v[20:21]
	v_pk_mul_f32 v[18:19], v[6:7], v[22:23]
	v_pk_mul_f32 v[24:25], v[4:5], v[24:25]
	v_pk_mul_f32 v[22:23], v[2:3], v[42:43]
	s_cbranch_vccnz .LBB0_879
	v_lshl_add_u64 v[46:47], v[114:115], 0, v[82:83]
	v_pk_fma_f32 v[44:45], v[104:105], v[20:21], v[16:17]
	v_pk_fma_f32 v[42:43], v[94:95], v[18:19], v[14:15]
	v_lshl_add_u64 v[46:47], v[46:47], 1, s[82:83]
	v_pk_fma_f32 v[48:49], v[102:103], v[24:25], v[12:13]
	v_pk_fma_f32 v[50:51], v[96:97], v[22:23], v[10:11]
	v_cvt_pk_bf16_f32 v42, v42, v43
	v_cvt_pk_bf16_f32 v43, v44, v45
	s_nop 0
	v_cvt_pk_bf16_f32 v44, v50, v51
	v_cvt_pk_bf16_f32 v45, v48, v49
	global_store_dwordx4 v[46:47], v[42:45], off sc1
	s_cbranch_execnz .LBB0_669
.LBB0_668:
	global_store_dwordx4 v[108:109], v[18:21], off offset:512 sc1
	global_store_dwordx4 v[108:109], v[22:25], off offset:528 sc1
.LBB0_669:
	ds_read_b32 v18, v0 offset:8704
	s_and_b64 vcc, exec, s[6:7]
	s_waitcnt lgkmcnt(0)
	v_pk_mul_f32 v[20:21], v[40:41], v[18:19] op_sel_hi:[1,0]
	v_pk_mul_f32 v[22:23], v[38:39], v[18:19] op_sel_hi:[1,0]
	v_pk_mul_f32 v[24:25], v[36:37], v[18:19] op_sel_hi:[1,0]
	v_pk_mul_f32 v[34:35], v[34:35], v[18:19] op_sel_hi:[1,0]
	v_pk_mul_f32 v[20:21], v[8:9], v[20:21]
	v_pk_mul_f32 v[18:19], v[6:7], v[22:23]
	v_pk_mul_f32 v[24:25], v[4:5], v[24:25]
	v_pk_mul_f32 v[22:23], v[2:3], v[34:35]
	s_cbranch_vccnz .LBB0_880
	v_lshl_add_u64 v[38:39], v[106:107], 0, v[82:83]
	v_pk_fma_f32 v[36:37], v[104:105], v[20:21], v[16:17]
	v_pk_fma_f32 v[34:35], v[94:95], v[18:19], v[14:15]
	v_lshl_add_u64 v[38:39], v[38:39], 1, s[82:83]
	v_pk_fma_f32 v[40:41], v[102:103], v[24:25], v[12:13]
	v_pk_fma_f32 v[42:43], v[96:97], v[22:23], v[10:11]
	v_cvt_pk_bf16_f32 v34, v34, v35
	v_cvt_pk_bf16_f32 v35, v36, v37
	s_nop 0
	v_cvt_pk_bf16_f32 v36, v42, v43
	v_cvt_pk_bf16_f32 v37, v40, v41
	global_store_dwordx4 v[38:39], v[34:37], off sc1
	s_cbranch_execnz .LBB0_672
.LBB0_671:
	global_store_dwordx4 v[100:101], v[18:21], off offset:512 sc1
	global_store_dwordx4 v[100:101], v[22:25], off offset:528 sc1
.LBB0_672:
	ds_read_b32 v18, v0 offset:8768
	s_and_b64 vcc, exec, s[6:7]
	s_waitcnt lgkmcnt(0)
	v_pk_mul_f32 v[20:21], v[32:33], v[18:19] op_sel_hi:[1,0]
	v_pk_mul_f32 v[22:23], v[30:31], v[18:19] op_sel_hi:[1,0]
	v_pk_mul_f32 v[24:25], v[28:29], v[18:19] op_sel_hi:[1,0]
	v_pk_mul_f32 v[26:27], v[26:27], v[18:19] op_sel_hi:[1,0]
	v_pk_mul_f32 v[20:21], v[8:9], v[20:21]
	v_pk_mul_f32 v[18:19], v[6:7], v[22:23]
	v_pk_mul_f32 v[24:25], v[4:5], v[24:25]
	v_pk_mul_f32 v[22:23], v[2:3], v[26:27]
	s_cbranch_vccnz .LBB0_881
	v_lshl_add_u64 v[30:31], v[98:99], 0, v[82:83]
	v_pk_fma_f32 v[28:29], v[104:105], v[20:21], v[16:17]
	v_pk_fma_f32 v[26:27], v[94:95], v[18:19], v[14:15]
	v_lshl_add_u64 v[30:31], v[30:31], 1, s[82:83]
	v_pk_fma_f32 v[32:33], v[102:103], v[24:25], v[12:13]
	v_pk_fma_f32 v[34:35], v[96:97], v[22:23], v[10:11]
	v_cvt_pk_bf16_f32 v26, v26, v27
	v_cvt_pk_bf16_f32 v27, v28, v29
	s_nop 0
	v_cvt_pk_bf16_f32 v28, v34, v35
	v_cvt_pk_bf16_f32 v29, v32, v33
	global_store_dwordx4 v[30:31], v[26:29], off sc1
	s_cbranch_execnz .LBB0_675
.LBB0_674:
	global_store_dwordx4 v[92:93], v[18:21], off offset:512 sc1
	global_store_dwordx4 v[92:93], v[22:25], off offset:528 sc1
.LBB0_675:
	ds_read_b32 v18, v0 offset:8832
	s_and_b64 vcc, exec, s[6:7]
	s_waitcnt lgkmcnt(0)
	v_pk_mul_f32 v[20:21], v[74:75], v[18:19] op_sel_hi:[1,0]
	v_pk_mul_f32 v[22:23], v[78:79], v[18:19] op_sel_hi:[1,0]
	v_pk_mul_f32 v[24:25], v[76:77], v[18:19] op_sel_hi:[1,0]
	v_pk_mul_f32 v[26:27], v[80:81], v[18:19] op_sel_hi:[1,0]
	v_pk_mul_f32 v[20:21], v[8:9], v[20:21]
	v_pk_mul_f32 v[18:19], v[6:7], v[22:23]
	v_pk_mul_f32 v[24:25], v[4:5], v[24:25]
	v_pk_mul_f32 v[22:23], v[2:3], v[26:27]
	s_cbranch_vccnz .LBB0_882
	v_lshl_add_u64 v[30:31], v[90:91], 0, v[82:83]
	v_pk_fma_f32 v[28:29], v[104:105], v[20:21], v[16:17]
	v_pk_fma_f32 v[26:27], v[94:95], v[18:19], v[14:15]
	v_lshl_add_u64 v[30:31], v[30:31], 1, s[82:83]
	v_pk_fma_f32 v[32:33], v[102:103], v[24:25], v[12:13]
	v_pk_fma_f32 v[34:35], v[96:97], v[22:23], v[10:11]
	v_cvt_pk_bf16_f32 v26, v26, v27
	v_cvt_pk_bf16_f32 v27, v28, v29
	s_nop 0
	v_cvt_pk_bf16_f32 v28, v34, v35
	v_cvt_pk_bf16_f32 v29, v32, v33
	global_store_dwordx4 v[30:31], v[26:29], off sc1
	s_cbranch_execnz .LBB0_678
.LBB0_677:
	global_store_dwordx4 v[86:87], v[18:21], off offset:512 sc1
	global_store_dwordx4 v[86:87], v[22:25], off offset:528 sc1
.LBB0_678:
	ds_read_b32 v0, v0 offset:8896
	s_and_b64 vcc, exec, s[6:7]
	s_waitcnt lgkmcnt(0)
	v_pk_mul_f32 v[18:19], v[150:151], v[0:1] op_sel_hi:[1,0]
	v_pk_mul_f32 v[20:21], v[154:155], v[0:1] op_sel_hi:[1,0]
	v_pk_mul_f32 v[22:23], v[152:153], v[0:1] op_sel_hi:[1,0]
	v_pk_mul_f32 v[24:25], v[156:157], v[0:1] op_sel_hi:[1,0]
	v_pk_mul_f32 v[8:9], v[8:9], v[18:19]
	v_pk_mul_f32 v[6:7], v[6:7], v[20:21]
	v_pk_mul_f32 v[4:5], v[4:5], v[22:23]
	v_pk_mul_f32 v[2:3], v[2:3], v[24:25]
	s_cbranch_vccnz .LBB0_883
	v_lshl_add_u64 v[18:19], v[84:85], 0, v[82:83]
	v_pk_fma_f32 v[14:15], v[94:95], v[6:7], v[14:15]
	v_pk_fma_f32 v[20:21], v[102:103], v[4:5], v[12:13]
	v_pk_fma_f32 v[12:13], v[96:97], v[2:3], v[10:11]
	v_cvt_pk_bf16_f32 v10, v14, v15
	v_lshl_add_u64 v[14:15], v[18:19], 1, s[82:83]
	v_pk_fma_f32 v[16:17], v[104:105], v[8:9], v[16:17]
	s_nop 0
	v_cvt_pk_bf16_f32 v11, v16, v17
	v_cvt_pk_bf16_f32 v12, v12, v13
	v_cvt_pk_bf16_f32 v13, v20, v21
	global_store_dwordx4 v[14:15], v[10:13], off sc1
	s_cbranch_execnz .LBB0_681
.LBB0_680:
	global_store_dwordx4 v[88:89], v[6:9], off offset:512 sc1
	global_store_dwordx4 v[88:89], v[2:5], off offset:528 sc1

.LBB0_695:
	v_mul_f32_e32 v147, 0xbfb8aa3b, v126
	v_exp_f32_e32 v147, v147
	v_lshl_add_u32 v146, s0, 8, v142
	v_lshl_or_b32 v148, s1, 7, v144
	v_readlane_b32 s0, v255, 11
	v_add_f32_e32 v147, 1.0, v147
	v_rcp_f32_e32 v147, v147
	v_readlane_b32 s1, v255, 12
	v_ashrrev_i32_e32 v149, 31, v148
	s_movk_i32 s4, 0x1600
	v_mul_f32_e32 v126, v126, v147
	v_mul_f32_e32 v122, v126, v122
	v_mul_f32_e32 v126, 0xbfb8aa3b, v127
	v_exp_f32_e32 v126, v126
	v_mov_b64_e32 v[140:141], s[0:1]
	v_mad_i64_i32 v[150:151], s[0:1], v146, s4, v[140:141]
	v_add_f32_e32 v126, 1.0, v126
	v_rcp_f32_e32 v126, v126
	s_andn2_b64 vcc, exec, s[6:7]
	v_mul_f32_e32 v126, v127, v126
	v_mul_f32_e32 v123, v126, v123
	v_mul_f32_e32 v126, 0xbfb8aa3b, v128
	v_exp_f32_e32 v126, v126
	s_nop 0
	v_add_f32_e32 v126, 1.0, v126
	v_rcp_f32_e32 v126, v126
	s_nop 0
	v_mul_f32_e32 v126, v128, v126
	v_mul_f32_e32 v124, v126, v124
	v_mul_f32_e32 v126, 0xbfb8aa3b, v129
	v_exp_f32_e32 v126, v126
	s_nop 0
	v_add_f32_e32 v126, 1.0, v126
	v_rcp_f32_e32 v126, v126
	s_nop 0
	v_mul_f32_e32 v126, v129, v126
	v_mul_f32_e32 v125, v126, v125
	v_mul_f32_e32 v126, 0xbfb8aa3b, v118
	v_exp_f32_e32 v126, v126
	s_nop 0
	v_add_f32_e32 v126, 1.0, v126
	v_rcp_f32_e32 v126, v126
	s_nop 0
	v_mul_f32_e32 v118, v118, v126
	v_mul_f32_e32 v118, v118, v114
	v_mul_f32_e32 v114, 0xbfb8aa3b, v119
	v_exp_f32_e32 v114, v114
	s_nop 0
	v_add_f32_e32 v114, 1.0, v114
	v_rcp_f32_e32 v114, v114
	s_nop 0
	v_mul_f32_e32 v114, v119, v114
	v_mul_f32_e32 v119, v114, v115
	v_mul_f32_e32 v114, 0xbfb8aa3b, v120
	v_exp_f32_e32 v114, v114
	s_nop 0
	v_add_f32_e32 v114, 1.0, v114
	v_rcp_f32_e32 v114, v114
	s_nop 0
	v_mul_f32_e32 v114, v120, v114
	v_mul_f32_e32 v126, v114, v116
	v_mul_f32_e32 v114, 0xbfb8aa3b, v121
	v_exp_f32_e32 v114, v114
	v_cvt_pk_bf16_f32 v116, v122, v123
	s_nop 0
	v_add_f32_e32 v114, 1.0, v114
	v_rcp_f32_e32 v114, v114
	s_nop 0
	v_mul_f32_e32 v114, v121, v114
	v_mul_f32_e32 v127, v114, v117
	v_lshlrev_b64 v[114:115], 1, v[148:149]
	v_lshl_add_u64 v[120:121], v[150:151], 0, v[114:115]
	v_cvt_pk_bf16_f32 v117, v124, v125
	v_cvt_pk_bf16_f32 v118, v118, v119
	v_cvt_pk_bf16_f32 v119, v126, v127
	global_store_dwordx4 v[120:121], v[116:119], off sc1
	s_nop 1
	v_mul_f32_e32 v118, 0xbfb8aa3b, v110
	v_exp_f32_e32 v118, v118
	v_or_b32_e32 v116, 16, v146
	v_mad_i64_i32 v[116:117], s[0:1], v116, s4, v[140:141]
	v_add_f32_e32 v118, 1.0, v118
	v_rcp_f32_e32 v118, v118
	s_nop 0
	v_mul_f32_e32 v110, v110, v118
	v_mul_f32_e32 v106, v110, v106
	v_mul_f32_e32 v110, 0xbfb8aa3b, v111
	v_exp_f32_e32 v110, v110
	s_nop 0
	v_add_f32_e32 v110, 1.0, v110
	v_rcp_f32_e32 v110, v110
	s_nop 0
	v_mul_f32_e32 v110, v111, v110
	v_mul_f32_e32 v107, v110, v107
	v_mul_f32_e32 v110, 0xbfb8aa3b, v112
	v_exp_f32_e32 v110, v110
	s_nop 0
	v_add_f32_e32 v110, 1.0, v110
	v_rcp_f32_e32 v110, v110
	s_nop 0
	v_mul_f32_e32 v110, v112, v110
	v_mul_f32_e32 v108, v110, v108
	v_mul_f32_e32 v110, 0xbfb8aa3b, v113
	v_exp_f32_e32 v110, v110
	s_nop 0
	v_add_f32_e32 v110, 1.0, v110
	v_rcp_f32_e32 v110, v110
	s_nop 0
	v_mul_f32_e32 v110, v113, v110
	v_mul_f32_e32 v109, v110, v109
	v_mul_f32_e32 v110, 0xbfb8aa3b, v102
	v_exp_f32_e32 v110, v110
	s_nop 0
	v_add_f32_e32 v110, 1.0, v110
	v_rcp_f32_e32 v110, v110
	s_nop 0
	v_mul_f32_e32 v102, v102, v110
	v_mul_f32_e32 v110, v102, v98
	v_mul_f32_e32 v98, 0xbfb8aa3b, v103
	v_exp_f32_e32 v98, v98
	s_nop 0
	v_add_f32_e32 v98, 1.0, v98
	v_rcp_f32_e32 v98, v98
	s_nop 0
	v_mul_f32_e32 v98, v103, v98
	v_mul_f32_e32 v111, v98, v99
	v_mul_f32_e32 v98, 0xbfb8aa3b, v104
	v_exp_f32_e32 v98, v98
	v_lshl_add_u64 v[102:103], v[116:117], 0, v[114:115]
	v_add_f32_e32 v98, 1.0, v98
	v_rcp_f32_e32 v98, v98
	s_nop 0
	v_mul_f32_e32 v98, v104, v98
	v_mul_f32_e32 v104, v98, v100
	v_mul_f32_e32 v98, 0xbfb8aa3b, v105
	v_exp_f32_e32 v98, v98
	s_nop 0
	v_add_f32_e32 v98, 1.0, v98
	v_rcp_f32_e32 v98, v98
	s_nop 0
	v_mul_f32_e32 v98, v105, v98
	v_mul_f32_e32 v101, v98, v101
	v_cvt_pk_bf16_f32 v98, v106, v107
	v_cvt_pk_bf16_f32 v99, v108, v109
	v_cvt_pk_bf16_f32 v100, v110, v111
	v_cvt_pk_bf16_f32 v101, v104, v101
	global_store_dwordx4 v[102:103], v[98:101], off sc1
	s_nop 1
	v_mul_f32_e32 v100, 0xbfb8aa3b, v94
	v_exp_f32_e32 v100, v100
	v_or_b32_e32 v98, 32, v146
	v_mad_i64_i32 v[98:99], s[0:1], v98, s4, v[140:141]
	v_add_f32_e32 v100, 1.0, v100
	v_rcp_f32_e32 v100, v100
	s_nop 0
	v_mul_f32_e32 v94, v94, v100
	v_mul_f32_e32 v90, v94, v90
	v_mul_f32_e32 v94, 0xbfb8aa3b, v95
	v_exp_f32_e32 v94, v94
	s_nop 0
	v_add_f32_e32 v94, 1.0, v94
	v_rcp_f32_e32 v94, v94
	s_nop 0
	v_mul_f32_e32 v94, v95, v94
	v_mul_f32_e32 v91, v94, v91
	v_mul_f32_e32 v94, 0xbfb8aa3b, v96
	v_exp_f32_e32 v94, v94
	s_nop 0
	v_add_f32_e32 v94, 1.0, v94
	v_rcp_f32_e32 v94, v94
	s_nop 0
	v_mul_f32_e32 v94, v96, v94
	v_mul_f32_e32 v92, v94, v92
	v_mul_f32_e32 v94, 0xbfb8aa3b, v97
	v_exp_f32_e32 v94, v94
	s_nop 0
	v_add_f32_e32 v94, 1.0, v94
	v_rcp_f32_e32 v94, v94
	s_nop 0
	v_mul_f32_e32 v94, v97, v94
	v_mul_f32_e32 v93, v94, v93
	v_mul_f32_e32 v94, 0xbfb8aa3b, v86
	v_exp_f32_e32 v94, v94
	s_nop 0
	v_add_f32_e32 v94, 1.0, v94
	v_rcp_f32_e32 v94, v94
	s_nop 0
	v_mul_f32_e32 v86, v86, v94
	v_mul_f32_e32 v94, v86, v82
	v_mul_f32_e32 v82, 0xbfb8aa3b, v87
	v_exp_f32_e32 v82, v82
	s_nop 0
	v_add_f32_e32 v82, 1.0, v82
	v_rcp_f32_e32 v82, v82
	s_nop 0
	v_mul_f32_e32 v82, v87, v82
	v_mul_f32_e32 v95, v82, v83
	v_mul_f32_e32 v82, 0xbfb8aa3b, v88
	v_exp_f32_e32 v82, v82
	v_lshl_add_u64 v[86:87], v[98:99], 0, v[114:115]
	v_add_f32_e32 v82, 1.0, v82
	v_rcp_f32_e32 v82, v82
	s_nop 0
	v_mul_f32_e32 v82, v88, v82
	v_mul_f32_e32 v88, v82, v84
	v_mul_f32_e32 v82, 0xbfb8aa3b, v89
	v_exp_f32_e32 v82, v82
	s_nop 0
	v_add_f32_e32 v82, 1.0, v82
	v_rcp_f32_e32 v82, v82
	s_nop 0
	v_mul_f32_e32 v82, v89, v82
	v_mul_f32_e32 v85, v82, v85
	v_cvt_pk_bf16_f32 v82, v90, v91
	v_cvt_pk_bf16_f32 v83, v92, v93
	v_cvt_pk_bf16_f32 v84, v94, v95
	v_cvt_pk_bf16_f32 v85, v88, v85
	global_store_dwordx4 v[86:87], v[82:85], off sc1
	s_nop 1
	v_mul_f32_e32 v84, 0xbfb8aa3b, v78
	v_exp_f32_e32 v84, v84
	v_or_b32_e32 v82, 48, v146
	v_mad_i64_i32 v[82:83], s[0:1], v82, s4, v[140:141]
	v_add_f32_e32 v84, 1.0, v84
	v_rcp_f32_e32 v84, v84
	s_nop 0
	v_mul_f32_e32 v78, v78, v84
	v_mul_f32_e32 v74, v78, v74
	v_mul_f32_e32 v78, 0xbfb8aa3b, v79
	v_exp_f32_e32 v78, v78
	s_nop 0
	v_add_f32_e32 v78, 1.0, v78
	v_rcp_f32_e32 v78, v78
	s_nop 0
	v_mul_f32_e32 v78, v79, v78
	v_mul_f32_e32 v75, v78, v75
	v_mul_f32_e32 v78, 0xbfb8aa3b, v80
	v_exp_f32_e32 v78, v78
	s_nop 0
	v_add_f32_e32 v78, 1.0, v78
	v_rcp_f32_e32 v78, v78
	s_nop 0
	v_mul_f32_e32 v78, v80, v78
	v_mul_f32_e32 v76, v78, v76
	v_mul_f32_e32 v78, 0xbfb8aa3b, v81
	v_exp_f32_e32 v78, v78
	s_nop 0
	v_add_f32_e32 v78, 1.0, v78
	v_rcp_f32_e32 v78, v78
	s_nop 0
	v_mul_f32_e32 v78, v81, v78
	v_mul_f32_e32 v77, v78, v77
	v_mul_f32_e32 v78, 0xbfb8aa3b, v70
	v_exp_f32_e32 v78, v78
	s_nop 0
	v_add_f32_e32 v78, 1.0, v78
	v_rcp_f32_e32 v78, v78
	s_nop 0
	v_mul_f32_e32 v70, v70, v78
	v_mul_f32_e32 v78, v70, v66
	v_mul_f32_e32 v66, 0xbfb8aa3b, v71
	v_exp_f32_e32 v66, v66
	s_nop 0
	v_add_f32_e32 v66, 1.0, v66
	v_rcp_f32_e32 v66, v66
	s_nop 0
	v_mul_f32_e32 v66, v71, v66
	v_mul_f32_e32 v79, v66, v67
	v_mul_f32_e32 v66, 0xbfb8aa3b, v72
	v_exp_f32_e32 v66, v66
	v_lshl_add_u64 v[70:71], v[82:83], 0, v[114:115]
	v_add_f32_e32 v66, 1.0, v66
	v_rcp_f32_e32 v66, v66
	s_nop 0
	v_mul_f32_e32 v66, v72, v66
	v_mul_f32_e32 v72, v66, v68
	v_mul_f32_e32 v66, 0xbfb8aa3b, v73
	v_exp_f32_e32 v66, v66
	s_nop 0
	v_add_f32_e32 v66, 1.0, v66
	v_rcp_f32_e32 v66, v66
	s_nop 0
	v_mul_f32_e32 v66, v73, v66
	v_mul_f32_e32 v69, v66, v69
	v_cvt_pk_bf16_f32 v66, v74, v75
	v_cvt_pk_bf16_f32 v67, v76, v77
	v_cvt_pk_bf16_f32 v68, v78, v79
	v_cvt_pk_bf16_f32 v69, v72, v69
	global_store_dwordx4 v[70:71], v[66:69], off sc1
	s_nop 1
	v_mul_f32_e32 v68, 0xbfb8aa3b, v62
	v_exp_f32_e32 v68, v68
	v_add_u32_e32 v66, 0x80, v146
	v_mad_i64_i32 v[66:67], s[0:1], v66, s4, v[140:141]
	v_add_f32_e32 v68, 1.0, v68
	v_rcp_f32_e32 v68, v68
	s_nop 0
	v_mul_f32_e32 v62, v62, v68
	v_mul_f32_e32 v58, v62, v58
	v_mul_f32_e32 v62, 0xbfb8aa3b, v63
	v_exp_f32_e32 v62, v62
	s_nop 0
	v_add_f32_e32 v62, 1.0, v62
	v_rcp_f32_e32 v62, v62
	s_nop 0
	v_mul_f32_e32 v62, v63, v62
	v_mul_f32_e32 v59, v62, v59
	v_mul_f32_e32 v62, 0xbfb8aa3b, v64
	v_exp_f32_e32 v62, v62
	s_nop 0
	v_add_f32_e32 v62, 1.0, v62
	v_rcp_f32_e32 v62, v62
	s_nop 0
	v_mul_f32_e32 v62, v64, v62
	v_mul_f32_e32 v60, v62, v60
	v_mul_f32_e32 v62, 0xbfb8aa3b, v65
	v_exp_f32_e32 v62, v62
	s_nop 0
	v_add_f32_e32 v62, 1.0, v62
	v_rcp_f32_e32 v62, v62
	s_nop 0
	v_mul_f32_e32 v62, v65, v62
	v_mul_f32_e32 v61, v62, v61
	v_mul_f32_e32 v62, 0xbfb8aa3b, v54
	v_exp_f32_e32 v62, v62
	s_nop 0
	v_add_f32_e32 v62, 1.0, v62
	v_rcp_f32_e32 v62, v62
	s_nop 0
	v_mul_f32_e32 v54, v54, v62
	v_mul_f32_e32 v62, v54, v50
	v_mul_f32_e32 v50, 0xbfb8aa3b, v55
	v_exp_f32_e32 v50, v50
	s_nop 0
	v_add_f32_e32 v50, 1.0, v50
	v_rcp_f32_e32 v50, v50
	s_nop 0
	v_mul_f32_e32 v50, v55, v50
	v_mul_f32_e32 v63, v50, v51
	v_mul_f32_e32 v50, 0xbfb8aa3b, v56
	v_exp_f32_e32 v50, v50
	v_lshl_add_u64 v[54:55], v[66:67], 0, v[114:115]
	v_add_f32_e32 v50, 1.0, v50
	v_rcp_f32_e32 v50, v50
	s_nop 0
	v_mul_f32_e32 v50, v56, v50
	v_mul_f32_e32 v56, v50, v52
	v_mul_f32_e32 v50, 0xbfb8aa3b, v57
	v_exp_f32_e32 v50, v50
	s_nop 0
	v_add_f32_e32 v50, 1.0, v50
	v_rcp_f32_e32 v50, v50
	s_nop 0
	v_mul_f32_e32 v50, v57, v50
	v_mul_f32_e32 v53, v50, v53
	v_cvt_pk_bf16_f32 v50, v58, v59
	v_cvt_pk_bf16_f32 v51, v60, v61
	v_cvt_pk_bf16_f32 v52, v62, v63
	v_cvt_pk_bf16_f32 v53, v56, v53
	global_store_dwordx4 v[54:55], v[50:53], off sc1
	s_nop 1
	v_mul_f32_e32 v52, 0xbfb8aa3b, v46
	v_exp_f32_e32 v52, v52
	v_add_u32_e32 v50, 0x90, v146
	v_mad_i64_i32 v[50:51], s[0:1], v50, s4, v[140:141]
	v_add_f32_e32 v52, 1.0, v52
	v_rcp_f32_e32 v52, v52
	s_nop 0
	v_mul_f32_e32 v46, v46, v52
	v_mul_f32_e32 v42, v46, v42
	v_mul_f32_e32 v46, 0xbfb8aa3b, v47
	v_exp_f32_e32 v46, v46
	s_nop 0
	v_add_f32_e32 v46, 1.0, v46
	v_rcp_f32_e32 v46, v46
	s_nop 0
	v_mul_f32_e32 v46, v47, v46
	v_mul_f32_e32 v43, v46, v43
	v_mul_f32_e32 v46, 0xbfb8aa3b, v48
	v_exp_f32_e32 v46, v46
	s_nop 0
	v_add_f32_e32 v46, 1.0, v46
	v_rcp_f32_e32 v46, v46
	s_nop 0
	v_mul_f32_e32 v46, v48, v46
	v_mul_f32_e32 v44, v46, v44
	v_mul_f32_e32 v46, 0xbfb8aa3b, v49
	v_exp_f32_e32 v46, v46
	s_nop 0
	v_add_f32_e32 v46, 1.0, v46
	v_rcp_f32_e32 v46, v46
	s_nop 0
	v_mul_f32_e32 v46, v49, v46
	v_mul_f32_e32 v45, v46, v45
	v_mul_f32_e32 v46, 0xbfb8aa3b, v38
	v_exp_f32_e32 v46, v46
	s_nop 0
	v_add_f32_e32 v46, 1.0, v46
	v_rcp_f32_e32 v46, v46
	s_nop 0
	v_mul_f32_e32 v38, v38, v46
	v_mul_f32_e32 v46, v38, v34
	v_mul_f32_e32 v34, 0xbfb8aa3b, v39
	v_exp_f32_e32 v34, v34
	s_nop 0
	v_add_f32_e32 v34, 1.0, v34
	v_rcp_f32_e32 v34, v34
	s_nop 0
	v_mul_f32_e32 v34, v39, v34
	v_mul_f32_e32 v47, v34, v35
	v_mul_f32_e32 v34, 0xbfb8aa3b, v40
	v_exp_f32_e32 v34, v34
	v_lshl_add_u64 v[38:39], v[50:51], 0, v[114:115]
	v_add_f32_e32 v34, 1.0, v34
	v_rcp_f32_e32 v34, v34
	s_nop 0
	v_mul_f32_e32 v34, v40, v34
	v_mul_f32_e32 v40, v34, v36
	v_mul_f32_e32 v34, 0xbfb8aa3b, v41
	v_exp_f32_e32 v34, v34
	s_nop 0
	v_add_f32_e32 v34, 1.0, v34
	v_rcp_f32_e32 v34, v34
	s_nop 0
	v_mul_f32_e32 v34, v41, v34
	v_mul_f32_e32 v37, v34, v37
	v_cvt_pk_bf16_f32 v34, v42, v43
	v_cvt_pk_bf16_f32 v35, v44, v45
	v_cvt_pk_bf16_f32 v36, v46, v47
	v_cvt_pk_bf16_f32 v37, v40, v37
	global_store_dwordx4 v[38:39], v[34:37], off sc1
	s_nop 1
	v_mul_f32_e32 v36, 0xbfb8aa3b, v30
	v_exp_f32_e32 v36, v36
	v_add_u32_e32 v34, 0xa0, v146
	v_mad_i64_i32 v[34:35], s[0:1], v34, s4, v[140:141]
	v_add_f32_e32 v36, 1.0, v36
	v_rcp_f32_e32 v36, v36
	s_nop 0
	v_mul_f32_e32 v30, v30, v36
	v_mul_f32_e32 v26, v30, v26
	v_mul_f32_e32 v30, 0xbfb8aa3b, v31
	v_exp_f32_e32 v30, v30
	s_nop 0
	v_add_f32_e32 v30, 1.0, v30
	v_rcp_f32_e32 v30, v30
	s_nop 0
	v_mul_f32_e32 v30, v31, v30
	v_mul_f32_e32 v27, v30, v27
	v_mul_f32_e32 v30, 0xbfb8aa3b, v32
	v_exp_f32_e32 v30, v30
	s_nop 0
	v_add_f32_e32 v30, 1.0, v30
	v_rcp_f32_e32 v30, v30
	s_nop 0
	v_mul_f32_e32 v30, v32, v30
	v_mul_f32_e32 v28, v30, v28
	v_mul_f32_e32 v30, 0xbfb8aa3b, v33
	v_exp_f32_e32 v30, v30
	s_nop 0
	v_add_f32_e32 v30, 1.0, v30
	v_rcp_f32_e32 v30, v30
	s_nop 0
	v_mul_f32_e32 v30, v33, v30
	v_mul_f32_e32 v29, v30, v29
	v_mul_f32_e32 v30, 0xbfb8aa3b, v22
	v_exp_f32_e32 v30, v30
	s_nop 0
	v_add_f32_e32 v30, 1.0, v30
	v_rcp_f32_e32 v30, v30
	s_nop 0
	v_mul_f32_e32 v22, v22, v30
	v_mul_f32_e32 v30, v22, v18
	v_mul_f32_e32 v18, 0xbfb8aa3b, v23
	v_exp_f32_e32 v18, v18
	s_nop 0
	v_add_f32_e32 v18, 1.0, v18
	v_rcp_f32_e32 v18, v18
	s_nop 0
	v_mul_f32_e32 v18, v23, v18
	v_mul_f32_e32 v31, v18, v19
	v_mul_f32_e32 v18, 0xbfb8aa3b, v24
	v_exp_f32_e32 v18, v18
	v_lshl_add_u64 v[22:23], v[34:35], 0, v[114:115]
	v_add_f32_e32 v18, 1.0, v18
	v_rcp_f32_e32 v18, v18
	s_nop 0
	v_mul_f32_e32 v18, v24, v18
	v_mul_f32_e32 v24, v18, v20
	v_mul_f32_e32 v18, 0xbfb8aa3b, v25
	v_exp_f32_e32 v18, v18
	s_nop 0
	v_add_f32_e32 v18, 1.0, v18
	v_rcp_f32_e32 v18, v18
	s_nop 0
	v_mul_f32_e32 v18, v25, v18
	v_mul_f32_e32 v21, v18, v21
	v_cvt_pk_bf16_f32 v18, v26, v27
	v_cvt_pk_bf16_f32 v19, v28, v29
	v_cvt_pk_bf16_f32 v20, v30, v31
	v_cvt_pk_bf16_f32 v21, v24, v21
	global_store_dwordx4 v[22:23], v[18:21], off sc1
	s_nop 1
	v_mul_f32_e32 v20, 0xbfb8aa3b, v14
	v_exp_f32_e32 v20, v20
	v_add_u32_e32 v18, 0xb0, v146
	v_mad_i64_i32 v[18:19], s[0:1], v18, s4, v[140:141]
	v_add_f32_e32 v20, 1.0, v20
	v_rcp_f32_e32 v20, v20
	s_mov_b64 s[0:1], -1
	v_mul_f32_e32 v14, v14, v20
	v_mul_f32_e32 v10, v14, v10
	v_mul_f32_e32 v14, 0xbfb8aa3b, v15
	v_exp_f32_e32 v14, v14
	s_nop 0
	v_add_f32_e32 v14, 1.0, v14
	v_rcp_f32_e32 v14, v14
	s_nop 0
	v_mul_f32_e32 v14, v15, v14
	v_mul_f32_e32 v11, v14, v11
	v_mul_f32_e32 v14, 0xbfb8aa3b, v16
	v_exp_f32_e32 v14, v14
	s_nop 0
	v_add_f32_e32 v14, 1.0, v14
	v_rcp_f32_e32 v14, v14
	s_nop 0
	v_mul_f32_e32 v14, v16, v14
	v_mul_f32_e32 v12, v14, v12
	v_mul_f32_e32 v14, 0xbfb8aa3b, v17
	v_exp_f32_e32 v14, v14
	s_nop 0
	v_add_f32_e32 v14, 1.0, v14
	v_rcp_f32_e32 v14, v14
	s_nop 0
	v_mul_f32_e32 v14, v17, v14
	v_mul_f32_e32 v13, v14, v13
	v_mul_f32_e32 v14, 0xbfb8aa3b, v6
	v_exp_f32_e32 v14, v14
	s_nop 0
	v_add_f32_e32 v14, 1.0, v14
	v_rcp_f32_e32 v14, v14
	s_nop 0
	v_mul_f32_e32 v6, v6, v14
	v_mul_f32_e32 v14, v6, v2
	v_mul_f32_e32 v2, 0xbfb8aa3b, v7
	v_exp_f32_e32 v2, v2
	s_nop 0
	v_add_f32_e32 v2, 1.0, v2
	v_rcp_f32_e32 v2, v2
	s_nop 0
	v_mul_f32_e32 v2, v7, v2
	v_mul_f32_e32 v15, v2, v3
	v_mul_f32_e32 v2, 0xbfb8aa3b, v8
	v_exp_f32_e32 v2, v2
	v_lshl_add_u64 v[6:7], v[18:19], 0, v[114:115]
	v_add_f32_e32 v2, 1.0, v2
	v_rcp_f32_e32 v2, v2
	s_nop 0
	v_mul_f32_e32 v2, v8, v2
	v_mul_f32_e32 v8, v2, v4
	v_mul_f32_e32 v2, 0xbfb8aa3b, v9
	v_exp_f32_e32 v2, v2
	s_nop 0
	v_add_f32_e32 v2, 1.0, v2
	v_rcp_f32_e32 v2, v2
	s_nop 0
	v_mul_f32_e32 v2, v9, v2
	v_mul_f32_e32 v5, v2, v5
	v_cvt_pk_bf16_f32 v2, v10, v11
	v_cvt_pk_bf16_f32 v3, v12, v13
	v_cvt_pk_bf16_f32 v4, v14, v15
	v_cvt_pk_bf16_f32 v5, v8, v5
	global_store_dwordx4 v[6:7], v[2:5], off sc1
	s_cbranch_vccnz .LBB0_688
	s_andn2_b64 vcc, exec, s[2:3]
	s_cbranch_vccnz .LBB0_687
	s_barrier
	s_branch .LBB0_687
